# both RWKV scans (sample+context) on the hand-written 4-compute+4-loader LDS-ring kernel with 8 rows per wave; phase D epilogue rewritten with all loads in flight; D K-loop two-deep register prefetch;
# speedup vs baseline: 1.1021x; 1.0387x over previous
.LBB0_480:
	v_cmp_lt_i32_e32 vcc, s90, v2
	s_cbranch_vccnz .LBB0_515
	v_lshlrev_b32_e32 v10, 5, v2
	v_add_u32_e32 v4, v10, v98
	s_waitcnt lgkmcnt(0)
	v_mov_b64_e32 v[2:3], s[28:29]
	v_mad_i64_i32 v[2:3], s[10:11], v4, s36, v[2:3]
	v_lshlrev_b32_e32 v130, 2, v100
	v_lshl_add_u64 v[2:3], v[2:3], 0, v[130:131]
	v_add_co_u32_e32 v2, vcc, 0x1000, v2
	s_nop 1
	v_addc_co_u32_e32 v3, vcc, 0, v3, vcc
	s_barrier
	v_add_u32_e32 v4, v10, v98
	v_mov_b64_e32 v[42:43], s[28:29]
	v_mad_i64_i32 v[42:43], s[10:11], v4, s36, v[42:43]
	v_lshl_add_u64 v[42:43], v[42:43], 0, v[130:131]
	v_add_co_u32_e32 v42, vcc, 0x1000, v42
	s_nop 1
	v_addc_co_u32_e32 v43, vcc, 0, v43, vcc
	global_load_dword v34, v[42:43], off offset:1024
	v_add_u32_e32 v4, v10, v227
	v_mov_b64_e32 v[42:43], s[28:29]
	v_mad_i64_i32 v[42:43], s[10:11], v4, s36, v[42:43]
	v_lshl_add_u64 v[42:43], v[42:43], 0, v[130:131]
	v_add_co_u32_e32 v42, vcc, 0x1000, v42
	s_nop 1
	v_addc_co_u32_e32 v43, vcc, 0, v43, vcc
	global_load_dword v35, v[42:43], off offset:1024
	v_add_u32_e32 v4, v10, v228
	v_mov_b64_e32 v[42:43], s[28:29]
	v_mad_i64_i32 v[42:43], s[10:11], v4, s36, v[42:43]
	v_lshl_add_u64 v[42:43], v[42:43], 0, v[130:131]
	v_add_co_u32_e32 v42, vcc, 0x1000, v42
	s_nop 1
	v_addc_co_u32_e32 v43, vcc, 0, v43, vcc
	global_load_dword v36, v[42:43], off offset:1024
	v_add_u32_e32 v4, v10, v229
	v_mov_b64_e32 v[42:43], s[28:29]
	v_mad_i64_i32 v[42:43], s[10:11], v4, s36, v[42:43]
	v_lshl_add_u64 v[42:43], v[42:43], 0, v[130:131]
	v_add_co_u32_e32 v42, vcc, 0x1000, v42
	s_nop 1
	v_addc_co_u32_e32 v43, vcc, 0, v43, vcc
	global_load_dword v37, v[42:43], off offset:1024
	v_add_u32_e32 v4, v10, v230
	v_mov_b64_e32 v[42:43], s[28:29]
	v_mad_i64_i32 v[42:43], s[10:11], v4, s36, v[42:43]
	v_lshl_add_u64 v[42:43], v[42:43], 0, v[130:131]
	v_add_co_u32_e32 v42, vcc, 0x1000, v42
	s_nop 1
	v_addc_co_u32_e32 v43, vcc, 0, v43, vcc
	global_load_dword v38, v[42:43], off offset:1024
	v_add_u32_e32 v4, v10, v231
	v_mov_b64_e32 v[42:43], s[28:29]
	v_mad_i64_i32 v[42:43], s[10:11], v4, s36, v[42:43]
	v_lshl_add_u64 v[42:43], v[42:43], 0, v[130:131]
	v_add_co_u32_e32 v42, vcc, 0x1000, v42
	s_nop 1
	v_addc_co_u32_e32 v43, vcc, 0, v43, vcc
	global_load_dword v39, v[42:43], off offset:1024
	v_add_u32_e32 v4, v10, v232
	v_mov_b64_e32 v[42:43], s[28:29]
	v_mad_i64_i32 v[42:43], s[10:11], v4, s36, v[42:43]
	v_lshl_add_u64 v[42:43], v[42:43], 0, v[130:131]
	v_add_co_u32_e32 v42, vcc, 0x1000, v42
	s_nop 1
	v_addc_co_u32_e32 v43, vcc, 0, v43, vcc
	global_load_dword v40, v[42:43], off offset:1024
	v_add_u32_e32 v4, v10, v233
	v_mov_b64_e32 v[42:43], s[28:29]
	v_mad_i64_i32 v[42:43], s[10:11], v4, s36, v[42:43]
	v_lshl_add_u64 v[42:43], v[42:43], 0, v[130:131]
	v_add_co_u32_e32 v42, vcc, 0x1000, v42
	s_nop 1
	v_addc_co_u32_e32 v43, vcc, 0, v43, vcc
	global_load_dword v41, v[42:43], off offset:1024
	s_waitcnt vmcnt(7)
	v_mov_b32_e32 v2, v34
	s_and_saveexec_b64 s[10:11], s[4:5]
	s_xor_b64 s[10:11], exec, s[10:11]
	s_cbranch_execz .LBB0_483
	s_waitcnt vmcnt(0)
	v_cvt_pk_bf16_f32 v2, v2, v131
	ds_write_b16 v234, v2 offset:4480

.LBB0_485:
	s_or_b64 exec, exec, s[10:11]
	v_add_u32_e32 v4, v10, v227
	s_waitcnt vmcnt(0)
	v_mov_b64_e32 v[2:3], s[28:29]
	v_mad_i64_i32 v[2:3], s[10:11], v4, s36, v[2:3]
	v_lshl_add_u64 v[2:3], v[2:3], 0, v[130:131]
	v_add_co_u32_e32 v2, vcc, 0x1000, v2
	s_nop 1
	v_addc_co_u32_e32 v3, vcc, 0, v3, vcc
	s_waitcnt vmcnt(6)
	v_mov_b32_e32 v2, v35
	s_and_saveexec_b64 s[10:11], s[4:5]
	s_xor_b64 s[10:11], exec, s[10:11]
	s_cbranch_execz .LBB0_487
	s_waitcnt vmcnt(0)
	v_cvt_pk_bf16_f32 v2, v2, v131
	ds_write_b16 v235, v2 offset:4480

.LBB0_489:
	s_or_b64 exec, exec, s[10:11]
	v_add_u32_e32 v4, v10, v228
	s_waitcnt vmcnt(0)
	v_mov_b64_e32 v[2:3], s[28:29]
	v_mad_i64_i32 v[2:3], s[10:11], v4, s36, v[2:3]
	v_lshl_add_u64 v[2:3], v[2:3], 0, v[130:131]
	v_add_co_u32_e32 v2, vcc, 0x1000, v2
	s_nop 1
	v_addc_co_u32_e32 v3, vcc, 0, v3, vcc
	s_waitcnt vmcnt(5)
	v_mov_b32_e32 v2, v36
	s_and_saveexec_b64 s[10:11], s[4:5]
	s_xor_b64 s[10:11], exec, s[10:11]
	s_cbranch_execz .LBB0_491
	s_waitcnt vmcnt(0)
	v_cvt_pk_bf16_f32 v2, v2, v131
	ds_write_b16 v236, v2 offset:4480

.LBB0_493:
	s_or_b64 exec, exec, s[10:11]
	v_add_u32_e32 v4, v10, v229
	s_waitcnt vmcnt(0)
	v_mov_b64_e32 v[2:3], s[28:29]
	v_mad_i64_i32 v[2:3], s[10:11], v4, s36, v[2:3]
	v_lshl_add_u64 v[2:3], v[2:3], 0, v[130:131]
	v_add_co_u32_e32 v2, vcc, 0x1000, v2
	s_nop 1
	v_addc_co_u32_e32 v3, vcc, 0, v3, vcc
	s_waitcnt vmcnt(4)
	v_mov_b32_e32 v2, v37
	s_and_saveexec_b64 s[10:11], s[4:5]
	s_xor_b64 s[10:11], exec, s[10:11]
	s_cbranch_execz .LBB0_495
	s_waitcnt vmcnt(0)
	v_cvt_pk_bf16_f32 v2, v2, v131
	ds_write_b16 v237, v2 offset:4480

.LBB0_497:
	s_or_b64 exec, exec, s[10:11]
	v_add_u32_e32 v4, v10, v230
	s_waitcnt vmcnt(0)
	v_mov_b64_e32 v[2:3], s[28:29]
	v_mad_i64_i32 v[2:3], s[10:11], v4, s36, v[2:3]
	v_lshl_add_u64 v[2:3], v[2:3], 0, v[130:131]
	v_add_co_u32_e32 v2, vcc, 0x1000, v2
	s_nop 1
	v_addc_co_u32_e32 v3, vcc, 0, v3, vcc
	s_waitcnt vmcnt(3)
	v_mov_b32_e32 v2, v38
	s_and_saveexec_b64 s[10:11], s[4:5]
	s_xor_b64 s[10:11], exec, s[10:11]
	s_cbranch_execz .LBB0_499
	s_waitcnt vmcnt(0)
	v_cvt_pk_bf16_f32 v2, v2, v131
	ds_write_b16 v238, v2 offset:4480

.LBB0_501:
	s_or_b64 exec, exec, s[10:11]
	v_add_u32_e32 v4, v10, v231
	s_waitcnt vmcnt(0)
	v_mov_b64_e32 v[2:3], s[28:29]
	v_mad_i64_i32 v[2:3], s[10:11], v4, s36, v[2:3]
	v_lshl_add_u64 v[2:3], v[2:3], 0, v[130:131]
	v_add_co_u32_e32 v2, vcc, 0x1000, v2
	s_nop 1
	v_addc_co_u32_e32 v3, vcc, 0, v3, vcc
	s_waitcnt vmcnt(2)
	v_mov_b32_e32 v2, v39
	s_and_saveexec_b64 s[10:11], s[4:5]
	s_xor_b64 s[10:11], exec, s[10:11]
	s_cbranch_execz .LBB0_503
	s_waitcnt vmcnt(0)
	v_cvt_pk_bf16_f32 v2, v2, v131
	ds_write_b16 v239, v2 offset:4480

.LBB0_505:
	s_or_b64 exec, exec, s[10:11]
	v_add_u32_e32 v4, v10, v232
	s_waitcnt vmcnt(0)
	v_mov_b64_e32 v[2:3], s[28:29]
	v_mad_i64_i32 v[2:3], s[10:11], v4, s36, v[2:3]
	v_lshl_add_u64 v[2:3], v[2:3], 0, v[130:131]
	v_add_co_u32_e32 v2, vcc, 0x1000, v2
	s_nop 1
	v_addc_co_u32_e32 v3, vcc, 0, v3, vcc
	s_waitcnt vmcnt(1)
	v_mov_b32_e32 v2, v40
	s_and_saveexec_b64 s[10:11], s[4:5]
	s_xor_b64 s[10:11], exec, s[10:11]
	s_cbranch_execz .LBB0_507
	s_waitcnt vmcnt(0)
	v_cvt_pk_bf16_f32 v2, v2, v131
	ds_write_b16 v240, v2 offset:4480

.LBB0_509:
	s_or_b64 exec, exec, s[10:11]
	v_add_u32_e32 v4, v10, v233
	s_waitcnt vmcnt(0)
	v_mov_b64_e32 v[2:3], s[28:29]
	v_mad_i64_i32 v[2:3], s[10:11], v4, s36, v[2:3]
	v_lshl_add_u64 v[2:3], v[2:3], 0, v[130:131]
	v_add_co_u32_e32 v2, vcc, 0x1000, v2
	s_nop 1
	v_addc_co_u32_e32 v3, vcc, 0, v3, vcc
	s_waitcnt vmcnt(0)
	v_mov_b32_e32 v2, v41
	s_and_saveexec_b64 s[10:11], s[4:5]
	s_xor_b64 s[10:11], exec, s[10:11]
	s_cbranch_execz .LBB0_511
	s_waitcnt vmcnt(0)
	v_cvt_pk_bf16_f32 v2, v2, v131
	ds_write_b16 v241, v2 offset:4480

.LBB0_568:
	s_or_b64 exec, exec, s[0:1]
	v_mov_b32_e32 v1, v0
	s_waitcnt lgkmcnt(0)
	s_barrier
	s_movk_i32 s0, 0x3000
	v_ashrrev_i32_e32 v89, 6, v1
	v_readlane_b32 s4, v253, 43
	v_mul_lo_u32 v2, v89, s0
	v_readlane_b32 s5, v253, 44
	v_add_u32_e32 v110, 0xf0, v2
	v_readfirstlane_b32 s0, v89
	v_readlane_b32 s70, v253, 52
	s_mov_b32 s71, s2
	s_lshr_b32 s70, s70, 1
	s_mov_b32 s25, 0
.Lsc_task_loop:
	s_cmp_ge_u32 s71, 320
	s_cbranch_scc1 .Lsc_done
	s_cmp_lt_u32 s71, 64
	s_cbranch_scc1 .Lsc_is_sample
	s_sub_u32 s20, s71, 64
	s_lshr_b32 s21, s20, 2
	s_lshl_b32 s22, s21, 8
	s_mov_b32 s23, 16
	s_branch .Lsc_decoded
.Lsc_is_sample:
	s_mov_b32 s20, s71
	s_lshr_b32 s21, s20, 2
	s_lshl_b32 s22, s21, 10
	s_add_u32 s22, s22, 0x4000
	s_mov_b32 s23, 64
.Lsc_decoded:
	s_bfe_u32 s24, s20, 0x10001
	s_cmp_ge_u32 s0, 4
	s_cbranch_scc1 .Lsc_loader
	s_and_b32 s22, s20, 1
	s_lshl_b32 s22, s22, 5
	s_lshl_b32 s1, s0, 3
	s_add_u32 s22, s22, s1
	v_and_b32_e32 v116, 15, v0
	v_bfe_u32 v117, v0, 4, 2
	v_lshlrev_b32_e32 v111, 4, v116
	v_add_u32_e32 v118, s22, v117
	v_add_u32_e32 v111, 0xf0, v111
	v_lshlrev_b32_e32 v112, 2, v118
	v_add_u32_e32 v112, 0x2f0, v112
	v_lshlrev_b32_e32 v114, 8, v118
	v_lshl_add_u32 v114, v116, 4, v114
	s_lshr_b32 s1, s21, 2
	s_and_b32 s4, s21, 3
	s_lshl_b32 s1, s1, 1
	s_add_u32 s1, s1, s80
	s_lshl_b32 s1, s1, 1
	s_add_u32 s1, s1, s24
	s_lshl_b32 s1, s1, 2
	s_add_u32 s1, s1, s4
	s_lshl_b32 s1, s1, 14
	s_cmp_lt_u32 s71, 64
	s_cbranch_scc0 .Lsc_ctx_init
	ds_read_b64 v[120:121], v131 offset:32
	s_waitcnt lgkmcnt(0)
	v_readfirstlane_b32 s4, v120
	v_readfirstlane_b32 s5, v121
	s_nop 3
	s_add_u32 s4, s4, s1
	s_addc_u32 s5, s5, 0
	s_nop 3
	global_load_dwordx4 v[2:5], v114, s[4:5]
	global_load_dwordx4 v[6:9], v114, s[4:5] offset:1024
	s_lshl_b32 s6, s21, 2
	s_lshr_b32 s6, s21, 2
	s_lshl_b32 s6, s6, 20
	s_add_u32 s6, s6, 0x400000
	s_branch .Lsc_init_done
.Lsc_ctx_init:
	v_mov_b32_e32 v2, 0
	v_mov_b32_e32 v3, 0
	v_mov_b32_e32 v4, 0
	v_mov_b32_e32 v5, 0
	v_mov_b32_e32 v6, 0
	v_mov_b32_e32 v7, 0
	v_mov_b32_e32 v8, 0
	v_mov_b32_e32 v9, 0
	s_lshr_b32 s6, s21, 2
	s_lshl_b32 s6, s6, 18
.Lsc_init_done:
	s_mov_b32 s9, s1
	v_readlane_b32 s4, v253, 47
	v_readlane_b32 s5, v253, 48
	s_lshl_b32 s1, s24, 23
	s_add_u32 s6, s6, s1
	s_and_b32 s1, s21, 3
	s_lshl_b32 s1, s1, 8
	s_add_u32 s6, s6, s1
	s_lshl_b32 s1, s22, 2
	s_add_u32 s6, s6, s1
	s_add_u32 s4, s4, s6
	s_addc_u32 s5, s5, 0
	s_cmp_eq_u32 s24, 1
	s_cselect_b64 s[10:11], -1, 0
	s_mov_b32 s6, 0x4000
	s_cselect_b32 s6, 0xffffc000, s6
	s_cselect_b32 s7, -1, 0
	s_lshl_b32 s1, s23, 4
	s_sub_u32 s1, s1, 1
	v_sub_u32_e32 v119, s1, v116
	v_cndmask_b32_e64 v119, v116, v119, s[10:11]
	v_lshlrev_b32_e32 v119, 10, v119
	v_lshl_add_u32 v113, v117, 2, v119
	s_mov_b32 s10, 0xcccccccc
	s_mov_b32 s11, 0xcccccccc
	s_mov_b32 s14, 0xaaaaaaaa
	s_mov_b32 s15, 0xaaaaaaaa
	s_mov_b32 s8, 0
	s_mov_b32 s1, s23
	v_mov_b32_e32 v106, v111
	v_mov_b32_e32 v107, v112
	s_barrier
	ds_read_b128 v[10:13], v106 offset:256
	ds_read_b128 v[14:17], v106 offset:12288
	ds_read_b128 v[18:21], v106 offset:12544
	ds_read_b128 v[22:25], v106 offset:12800
	ds_read_b128 v[26:29], v106 offset:0
	ds_read_b32 v30, v107 offset:0
	ds_read_b32 v32, v107 offset:16
	ds_read_b128 v[34:37], v106 offset:1024
	ds_read_b128 v[38:41], v106 offset:13056
	ds_read_b128 v[42:45], v106 offset:13312
	ds_read_b128 v[46:49], v106 offset:13568
	ds_read_b128 v[50:53], v106 offset:768
	ds_read_b32 v54, v107 offset:768
	ds_read_b32 v56, v107 offset:784
	s_waitcnt vmcnt(0)
.Lsc_c_loop:
	s_barrier
	s_add_u32 s20, s8, 0x6000
	s_cmp_eq_u32 s20, 0x1e000
	s_cselect_b32 s20, 0, s20
	v_add_u32_e32 v108, s20, v111
	v_add_u32_e32 v109, s20, v112
	s_waitcnt lgkmcnt(7)
	v_pk_mul_f32 v[86:87], v[4:5], v[12:13]
	v_pk_mul_f32 v[90:91], v[8:9], v[12:13]
	v_pk_fma_f32 v[86:87], v[2:3], v[10:11], v[86:87]
	v_pk_fma_f32 v[90:91], v[6:7], v[10:11], v[90:91]
	v_add_f32_e32 v82, v86, v87
	v_add_f32_e32 v84, v90, v91
	ds_read_b128 v[58:61], v106 offset:1792
	v_add_f32_dpp v82, v82, v82 row_ror:8 row_mask:0xf bank_mask:0xf
	v_add_f32_dpp v84, v84, v84 row_ror:8 row_mask:0xf bank_mask:0xf
	ds_read_b128 v[62:65], v106 offset:13824
	v_add_f32_dpp v82, v82, v82 row_ror:4 row_mask:0xf bank_mask:0xf
	v_add_f32_dpp v84, v84, v84 row_ror:4 row_mask:0xf bank_mask:0xf
	v_pk_mul_f32 v[98:99], v[24:25], v[30:31] op_sel_hi:[1,0]
	v_add_f32_dpp v82, v82, v82 row_ror:2 row_mask:0xf bank_mask:0xf
	v_add_f32_dpp v84, v84, v84 row_ror:2 row_mask:0xf bank_mask:0xf
	v_pk_mul_f32 v[102:103], v[24:25], v[32:33] op_sel_hi:[1,0]
	ds_read_b128 v[66:69], v106 offset:14080
	ds_read_b128 v[70:73], v106 offset:14336
	v_pk_mul_f32 v[96:97], v[22:23], v[30:31] op_sel_hi:[1,0]
	v_pk_fma_f32 v[98:99], v[4:5], v[16:17], v[98:99]
	v_pk_mul_f32 v[100:101], v[22:23], v[32:33] op_sel_hi:[1,0]
	v_pk_fma_f32 v[102:103], v[8:9], v[16:17], v[102:103]
	ds_read_b128 v[74:77], v106 offset:1536
	v_add_f32_dpp v82, v82, v82 row_ror:1 row_mask:0xf bank_mask:0xf
	v_add_f32_dpp v84, v84, v84 row_ror:1 row_mask:0xf bank_mask:0xf
	ds_read_b32 v78, v107 offset:1536
	v_pk_fma_f32 v[96:97], v[2:3], v[14:15], v[96:97]
	v_pk_fma_f32 v[4:5], v[20:21], v[82:83], v[98:99] op_sel_hi:[1,0,1]
	v_pk_fma_f32 v[100:101], v[6:7], v[14:15], v[100:101]
	v_pk_fma_f32 v[8:9], v[20:21], v[84:85], v[102:103] op_sel_hi:[1,0,1]
	ds_read_b32 v80, v107 offset:1552
	s_waitcnt lgkmcnt(7)
	v_pk_fma_f32 v[2:3], v[18:19], v[82:83], v[96:97] op_sel_hi:[1,0,1]
	v_pk_fma_f32 v[6:7], v[18:19], v[84:85], v[100:101] op_sel_hi:[1,0,1]
	v_pk_mul_f32 v[86:87], v[4:5], v[36:37]
	v_pk_mul_f32 v[90:91], v[8:9], v[36:37]
	v_pk_fma_f32 v[86:87], v[2:3], v[34:35], v[86:87]
	v_pk_fma_f32 v[90:91], v[6:7], v[34:35], v[90:91]
	v_add_f32_e32 v82, v86, v87
	v_add_f32_e32 v84, v90, v91
	ds_read_b128 v[136:139], v106 offset:2560
	v_add_f32_dpp v82, v82, v82 row_ror:8 row_mask:0xf bank_mask:0xf
	v_add_f32_dpp v84, v84, v84 row_ror:8 row_mask:0xf bank_mask:0xf
	ds_read_b128 v[140:143], v106 offset:14592
	v_add_f32_dpp v82, v82, v82 row_ror:4 row_mask:0xf bank_mask:0xf
	v_add_f32_dpp v84, v84, v84 row_ror:4 row_mask:0xf bank_mask:0xf
	v_pk_mul_f32 v[98:99], v[48:49], v[54:55] op_sel_hi:[1,0]
	v_add_f32_dpp v82, v82, v82 row_ror:2 row_mask:0xf bank_mask:0xf
	v_add_f32_dpp v84, v84, v84 row_ror:2 row_mask:0xf bank_mask:0xf
	v_pk_mul_f32 v[102:103], v[48:49], v[56:57] op_sel_hi:[1,0]
	ds_read_b128 v[144:147], v106 offset:14848
	ds_read_b128 v[148:151], v106 offset:15104
	v_pk_mul_f32 v[96:97], v[46:47], v[54:55] op_sel_hi:[1,0]
	v_pk_fma_f32 v[98:99], v[4:5], v[40:41], v[98:99]
	v_pk_mul_f32 v[100:101], v[46:47], v[56:57] op_sel_hi:[1,0]
	v_pk_fma_f32 v[102:103], v[8:9], v[40:41], v[102:103]
	ds_read_b128 v[152:155], v106 offset:2304
	v_pk_mul_f32 v[92:93], v[4:5], v[28:29]
	v_pk_mul_f32 v[94:95], v[8:9], v[28:29]
	v_add_f32_dpp v82, v82, v82 row_ror:1 row_mask:0xf bank_mask:0xf
	v_add_f32_dpp v84, v84, v84 row_ror:1 row_mask:0xf bank_mask:0xf
	ds_read_b32 v156, v107 offset:2304
	v_pk_fma_f32 v[96:97], v[2:3], v[38:39], v[96:97]
	v_pk_fma_f32 v[4:5], v[44:45], v[82:83], v[98:99] op_sel_hi:[1,0,1]
	v_pk_fma_f32 v[100:101], v[6:7], v[38:39], v[100:101]
	v_pk_fma_f32 v[8:9], v[44:45], v[84:85], v[102:103] op_sel_hi:[1,0,1]
	ds_read_b32 v158, v107 offset:2320
	v_pk_fma_f32 v[92:93], v[2:3], v[26:27], v[92:93]
	v_pk_fma_f32 v[94:95], v[6:7], v[26:27], v[94:95]
	s_waitcnt lgkmcnt(7)
	v_pk_fma_f32 v[2:3], v[42:43], v[82:83], v[96:97] op_sel_hi:[1,0,1]
	v_pk_fma_f32 v[6:7], v[42:43], v[84:85], v[100:101] op_sel_hi:[1,0,1]
	v_pk_mul_f32 v[86:87], v[4:5], v[60:61]
	v_pk_mul_f32 v[90:91], v[8:9], v[60:61]
	v_pk_fma_f32 v[86:87], v[2:3], v[58:59], v[86:87]
	v_pk_fma_f32 v[90:91], v[6:7], v[58:59], v[90:91]
	v_add_f32_e32 v82, v86, v87
	v_add_f32_e32 v84, v90, v91
	v_pk_mul_f32 v[98:99], v[72:73], v[78:79] op_sel_hi:[1,0]
	v_add_f32_dpp v82, v82, v82 row_ror:8 row_mask:0xf bank_mask:0xf
	v_add_f32_dpp v84, v84, v84 row_ror:8 row_mask:0xf bank_mask:0xf
	v_add_f32_e32 v160, v92, v93
	v_add_f32_dpp v82, v82, v82 row_ror:4 row_mask:0xf bank_mask:0xf
	v_add_f32_dpp v84, v84, v84 row_ror:4 row_mask:0xf bank_mask:0xf
	v_pk_mul_f32 v[102:103], v[72:73], v[80:81] op_sel_hi:[1,0]
	v_add_f32_dpp v82, v82, v82 row_ror:2 row_mask:0xf bank_mask:0xf
	v_add_f32_dpp v84, v84, v84 row_ror:2 row_mask:0xf bank_mask:0xf
	v_add_f32_e32 v190, v94, v95
	ds_read_b128 v[10:13], v106 offset:3328
	ds_read_b128 v[14:17], v106 offset:15360
	ds_read_b128 v[18:21], v106 offset:15616
	ds_read_b128 v[22:25], v106 offset:15872
	v_pk_mul_f32 v[96:97], v[70:71], v[78:79] op_sel_hi:[1,0]
	v_pk_fma_f32 v[98:99], v[4:5], v[64:65], v[98:99]
	v_pk_mul_f32 v[100:101], v[70:71], v[80:81] op_sel_hi:[1,0]
	v_pk_fma_f32 v[102:103], v[8:9], v[64:65], v[102:103]
	ds_read_b128 v[26:29], v106 offset:3072
	v_pk_mul_f32 v[92:93], v[4:5], v[52:53]
	v_pk_mul_f32 v[94:95], v[8:9], v[52:53]
	v_add_f32_dpp v82, v82, v82 row_ror:1 row_mask:0xf bank_mask:0xf
	v_add_f32_dpp v84, v84, v84 row_ror:1 row_mask:0xf bank_mask:0xf
	ds_read_b32 v30, v107 offset:3072
	v_pk_fma_f32 v[96:97], v[2:3], v[62:63], v[96:97]
	v_pk_fma_f32 v[4:5], v[68:69], v[82:83], v[98:99] op_sel_hi:[1,0,1]
	v_pk_fma_f32 v[100:101], v[6:7], v[62:63], v[100:101]
	v_pk_fma_f32 v[8:9], v[68:69], v[84:85], v[102:103] op_sel_hi:[1,0,1]
	ds_read_b32 v32, v107 offset:3088
	v_pk_fma_f32 v[92:93], v[2:3], v[50:51], v[92:93]
	v_pk_fma_f32 v[94:95], v[6:7], v[50:51], v[94:95]
	s_waitcnt lgkmcnt(7)
	v_pk_fma_f32 v[2:3], v[66:67], v[82:83], v[96:97] op_sel_hi:[1,0,1]
	v_pk_fma_f32 v[6:7], v[66:67], v[84:85], v[100:101] op_sel_hi:[1,0,1]
	v_pk_mul_f32 v[86:87], v[4:5], v[138:139]
	v_pk_mul_f32 v[90:91], v[8:9], v[138:139]
	v_pk_fma_f32 v[86:87], v[2:3], v[136:137], v[86:87]
	v_pk_fma_f32 v[90:91], v[6:7], v[136:137], v[90:91]
	v_add_f32_e32 v82, v86, v87
	v_add_f32_e32 v84, v90, v91
	v_pk_mul_f32 v[98:99], v[150:151], v[156:157] op_sel_hi:[1,0]
	v_add_f32_dpp v82, v82, v82 row_ror:8 row_mask:0xf bank_mask:0xf
	v_add_f32_dpp v84, v84, v84 row_ror:8 row_mask:0xf bank_mask:0xf
	v_add_f32_e32 v161, v92, v93
	v_add_f32_dpp v82, v82, v82 row_ror:4 row_mask:0xf bank_mask:0xf
	v_add_f32_dpp v84, v84, v84 row_ror:4 row_mask:0xf bank_mask:0xf
	v_pk_mul_f32 v[102:103], v[150:151], v[158:159] op_sel_hi:[1,0]
	v_add_f32_dpp v82, v82, v82 row_ror:2 row_mask:0xf bank_mask:0xf
	v_add_f32_dpp v84, v84, v84 row_ror:2 row_mask:0xf bank_mask:0xf
	v_add_f32_e32 v191, v94, v95
	ds_read_b128 v[34:37], v106 offset:4096
	ds_read_b128 v[38:41], v106 offset:16128
	ds_read_b128 v[42:45], v106 offset:16384
	ds_read_b128 v[46:49], v106 offset:16640
	v_pk_mul_f32 v[96:97], v[148:149], v[156:157] op_sel_hi:[1,0]
	v_pk_fma_f32 v[98:99], v[4:5], v[142:143], v[98:99]
	v_pk_mul_f32 v[100:101], v[148:149], v[158:159] op_sel_hi:[1,0]
	v_pk_fma_f32 v[102:103], v[8:9], v[142:143], v[102:103]
	ds_read_b128 v[50:53], v106 offset:3840
	v_pk_mul_f32 v[92:93], v[4:5], v[76:77]
	v_pk_mul_f32 v[94:95], v[8:9], v[76:77]
	v_add_f32_dpp v82, v82, v82 row_ror:1 row_mask:0xf bank_mask:0xf
	v_add_f32_dpp v84, v84, v84 row_ror:1 row_mask:0xf bank_mask:0xf
	ds_read_b32 v54, v107 offset:3840
	v_pk_fma_f32 v[96:97], v[2:3], v[140:141], v[96:97]
	v_pk_fma_f32 v[4:5], v[146:147], v[82:83], v[98:99] op_sel_hi:[1,0,1]
	v_pk_fma_f32 v[100:101], v[6:7], v[140:141], v[100:101]
	v_pk_fma_f32 v[8:9], v[146:147], v[84:85], v[102:103] op_sel_hi:[1,0,1]
	ds_read_b32 v56, v107 offset:3856
	v_pk_fma_f32 v[92:93], v[2:3], v[74:75], v[92:93]
	v_pk_fma_f32 v[94:95], v[6:7], v[74:75], v[94:95]
	s_waitcnt lgkmcnt(7)
	v_pk_fma_f32 v[2:3], v[144:145], v[82:83], v[96:97] op_sel_hi:[1,0,1]
	v_pk_fma_f32 v[6:7], v[144:145], v[84:85], v[100:101] op_sel_hi:[1,0,1]
	v_pk_mul_f32 v[86:87], v[4:5], v[12:13]
	v_pk_mul_f32 v[90:91], v[8:9], v[12:13]
	v_pk_fma_f32 v[86:87], v[2:3], v[10:11], v[86:87]
	v_pk_fma_f32 v[90:91], v[6:7], v[10:11], v[90:91]
	v_add_f32_e32 v82, v86, v87
	v_add_f32_e32 v84, v90, v91
	v_pk_mul_f32 v[98:99], v[24:25], v[30:31] op_sel_hi:[1,0]
	v_add_f32_dpp v82, v82, v82 row_ror:8 row_mask:0xf bank_mask:0xf
	v_add_f32_dpp v84, v84, v84 row_ror:8 row_mask:0xf bank_mask:0xf
	v_add_f32_e32 v162, v92, v93
	v_add_f32_dpp v82, v82, v82 row_ror:4 row_mask:0xf bank_mask:0xf
	v_add_f32_dpp v84, v84, v84 row_ror:4 row_mask:0xf bank_mask:0xf
	v_pk_mul_f32 v[102:103], v[24:25], v[32:33] op_sel_hi:[1,0]
	v_add_f32_dpp v82, v82, v82 row_ror:2 row_mask:0xf bank_mask:0xf
	v_add_f32_dpp v84, v84, v84 row_ror:2 row_mask:0xf bank_mask:0xf
	v_add_f32_e32 v192, v94, v95
	ds_read_b128 v[58:61], v106 offset:4864
	ds_read_b128 v[62:65], v106 offset:16896
	ds_read_b128 v[66:69], v106 offset:17152
	ds_read_b128 v[70:73], v106 offset:17408
	v_pk_mul_f32 v[96:97], v[22:23], v[30:31] op_sel_hi:[1,0]
	v_pk_fma_f32 v[98:99], v[4:5], v[16:17], v[98:99]
	v_pk_mul_f32 v[100:101], v[22:23], v[32:33] op_sel_hi:[1,0]
	v_pk_fma_f32 v[102:103], v[8:9], v[16:17], v[102:103]
	ds_read_b128 v[74:77], v106 offset:4608
	v_pk_mul_f32 v[92:93], v[4:5], v[154:155]
	v_pk_mul_f32 v[94:95], v[8:9], v[154:155]
	v_add_f32_dpp v82, v82, v82 row_ror:1 row_mask:0xf bank_mask:0xf
	v_add_f32_dpp v84, v84, v84 row_ror:1 row_mask:0xf bank_mask:0xf
	ds_read_b32 v78, v107 offset:4608
	v_pk_fma_f32 v[96:97], v[2:3], v[14:15], v[96:97]
	v_pk_fma_f32 v[4:5], v[20:21], v[82:83], v[98:99] op_sel_hi:[1,0,1]
	v_pk_fma_f32 v[100:101], v[6:7], v[14:15], v[100:101]
	v_pk_fma_f32 v[8:9], v[20:21], v[84:85], v[102:103] op_sel_hi:[1,0,1]
	ds_read_b32 v80, v107 offset:4624
	v_pk_fma_f32 v[92:93], v[2:3], v[152:153], v[92:93]
	v_pk_fma_f32 v[94:95], v[6:7], v[152:153], v[94:95]
	s_waitcnt lgkmcnt(7)
	v_pk_fma_f32 v[2:3], v[18:19], v[82:83], v[96:97] op_sel_hi:[1,0,1]
	v_pk_fma_f32 v[6:7], v[18:19], v[84:85], v[100:101] op_sel_hi:[1,0,1]
	v_pk_mul_f32 v[86:87], v[4:5], v[36:37]
	v_pk_mul_f32 v[90:91], v[8:9], v[36:37]
	v_pk_fma_f32 v[86:87], v[2:3], v[34:35], v[86:87]
	v_pk_fma_f32 v[90:91], v[6:7], v[34:35], v[90:91]
	v_add_f32_e32 v82, v86, v87
	v_add_f32_e32 v84, v90, v91
	v_pk_mul_f32 v[98:99], v[48:49], v[54:55] op_sel_hi:[1,0]
	v_add_f32_dpp v82, v82, v82 row_ror:8 row_mask:0xf bank_mask:0xf
	v_add_f32_dpp v84, v84, v84 row_ror:8 row_mask:0xf bank_mask:0xf
	v_add_f32_e32 v163, v92, v93
	v_add_f32_dpp v82, v82, v82 row_ror:4 row_mask:0xf bank_mask:0xf
	v_add_f32_dpp v84, v84, v84 row_ror:4 row_mask:0xf bank_mask:0xf
	v_pk_mul_f32 v[102:103], v[48:49], v[56:57] op_sel_hi:[1,0]
	v_add_f32_dpp v82, v82, v82 row_ror:2 row_mask:0xf bank_mask:0xf
	v_add_f32_dpp v84, v84, v84 row_ror:2 row_mask:0xf bank_mask:0xf
	v_add_f32_e32 v193, v94, v95
	ds_read_b128 v[136:139], v106 offset:5632
	ds_read_b128 v[140:143], v106 offset:17664
	ds_read_b128 v[144:147], v106 offset:17920
	ds_read_b128 v[148:151], v106 offset:18176
	v_pk_mul_f32 v[96:97], v[46:47], v[54:55] op_sel_hi:[1,0]
	v_pk_fma_f32 v[98:99], v[4:5], v[40:41], v[98:99]
	v_pk_mul_f32 v[100:101], v[46:47], v[56:57] op_sel_hi:[1,0]
	v_pk_fma_f32 v[102:103], v[8:9], v[40:41], v[102:103]
	ds_read_b128 v[152:155], v106 offset:5376
	v_pk_mul_f32 v[92:93], v[4:5], v[28:29]
	v_pk_mul_f32 v[94:95], v[8:9], v[28:29]
	v_add_f32_dpp v82, v82, v82 row_ror:1 row_mask:0xf bank_mask:0xf
	v_add_f32_dpp v84, v84, v84 row_ror:1 row_mask:0xf bank_mask:0xf
	ds_read_b32 v156, v107 offset:5376
	v_pk_fma_f32 v[96:97], v[2:3], v[38:39], v[96:97]
	v_pk_fma_f32 v[4:5], v[44:45], v[82:83], v[98:99] op_sel_hi:[1,0,1]
	v_pk_fma_f32 v[100:101], v[6:7], v[38:39], v[100:101]
	v_pk_fma_f32 v[8:9], v[44:45], v[84:85], v[102:103] op_sel_hi:[1,0,1]
	ds_read_b32 v158, v107 offset:5392
	v_pk_fma_f32 v[92:93], v[2:3], v[26:27], v[92:93]
	v_pk_fma_f32 v[94:95], v[6:7], v[26:27], v[94:95]
	s_waitcnt lgkmcnt(7)
	v_pk_fma_f32 v[2:3], v[42:43], v[82:83], v[96:97] op_sel_hi:[1,0,1]
	v_pk_fma_f32 v[6:7], v[42:43], v[84:85], v[100:101] op_sel_hi:[1,0,1]
	v_pk_mul_f32 v[86:87], v[4:5], v[60:61]
	v_pk_mul_f32 v[90:91], v[8:9], v[60:61]
	v_pk_fma_f32 v[86:87], v[2:3], v[58:59], v[86:87]
	v_pk_fma_f32 v[90:91], v[6:7], v[58:59], v[90:91]
	v_add_f32_e32 v82, v86, v87
	v_add_f32_e32 v84, v90, v91
	v_pk_mul_f32 v[98:99], v[72:73], v[78:79] op_sel_hi:[1,0]
	v_add_f32_dpp v82, v82, v82 row_ror:8 row_mask:0xf bank_mask:0xf
	v_add_f32_dpp v84, v84, v84 row_ror:8 row_mask:0xf bank_mask:0xf
	v_add_f32_e32 v164, v92, v93
	v_add_f32_dpp v82, v82, v82 row_ror:4 row_mask:0xf bank_mask:0xf
	v_add_f32_dpp v84, v84, v84 row_ror:4 row_mask:0xf bank_mask:0xf
	v_pk_mul_f32 v[102:103], v[72:73], v[80:81] op_sel_hi:[1,0]
	v_add_f32_dpp v82, v82, v82 row_ror:2 row_mask:0xf bank_mask:0xf
	v_add_f32_dpp v84, v84, v84 row_ror:2 row_mask:0xf bank_mask:0xf
	v_add_f32_e32 v194, v94, v95
	ds_read_b128 v[10:13], v106 offset:6400
	ds_read_b128 v[14:17], v106 offset:18432
	ds_read_b128 v[18:21], v106 offset:18688
	ds_read_b128 v[22:25], v106 offset:18944
	v_pk_mul_f32 v[96:97], v[70:71], v[78:79] op_sel_hi:[1,0]
	v_pk_fma_f32 v[98:99], v[4:5], v[64:65], v[98:99]
	v_pk_mul_f32 v[100:101], v[70:71], v[80:81] op_sel_hi:[1,0]
	v_pk_fma_f32 v[102:103], v[8:9], v[64:65], v[102:103]
	ds_read_b128 v[26:29], v106 offset:6144
	v_pk_mul_f32 v[92:93], v[4:5], v[52:53]
	v_pk_mul_f32 v[94:95], v[8:9], v[52:53]
	v_add_f32_dpp v82, v82, v82 row_ror:1 row_mask:0xf bank_mask:0xf
	v_add_f32_dpp v84, v84, v84 row_ror:1 row_mask:0xf bank_mask:0xf
	ds_read_b32 v30, v107 offset:6144
	v_pk_fma_f32 v[96:97], v[2:3], v[62:63], v[96:97]
	v_pk_fma_f32 v[4:5], v[68:69], v[82:83], v[98:99] op_sel_hi:[1,0,1]
	v_pk_fma_f32 v[100:101], v[6:7], v[62:63], v[100:101]
	v_pk_fma_f32 v[8:9], v[68:69], v[84:85], v[102:103] op_sel_hi:[1,0,1]
	ds_read_b32 v32, v107 offset:6160
	v_pk_fma_f32 v[92:93], v[2:3], v[50:51], v[92:93]
	v_pk_fma_f32 v[94:95], v[6:7], v[50:51], v[94:95]
	s_waitcnt lgkmcnt(7)
	v_pk_fma_f32 v[2:3], v[66:67], v[82:83], v[96:97] op_sel_hi:[1,0,1]
	v_pk_fma_f32 v[6:7], v[66:67], v[84:85], v[100:101] op_sel_hi:[1,0,1]
	v_pk_mul_f32 v[86:87], v[4:5], v[138:139]
	v_pk_mul_f32 v[90:91], v[8:9], v[138:139]
	v_pk_fma_f32 v[86:87], v[2:3], v[136:137], v[86:87]
	v_pk_fma_f32 v[90:91], v[6:7], v[136:137], v[90:91]
	v_add_f32_e32 v82, v86, v87
	v_add_f32_e32 v84, v90, v91
	v_pk_mul_f32 v[98:99], v[150:151], v[156:157] op_sel_hi:[1,0]
	v_add_f32_dpp v82, v82, v82 row_ror:8 row_mask:0xf bank_mask:0xf
	v_add_f32_dpp v84, v84, v84 row_ror:8 row_mask:0xf bank_mask:0xf
	v_add_f32_e32 v165, v92, v93
	v_add_f32_dpp v82, v82, v82 row_ror:4 row_mask:0xf bank_mask:0xf
	v_add_f32_dpp v84, v84, v84 row_ror:4 row_mask:0xf bank_mask:0xf
	v_pk_mul_f32 v[102:103], v[150:151], v[158:159] op_sel_hi:[1,0]
	v_add_f32_dpp v82, v82, v82 row_ror:2 row_mask:0xf bank_mask:0xf
	v_add_f32_dpp v84, v84, v84 row_ror:2 row_mask:0xf bank_mask:0xf
	v_add_f32_e32 v195, v94, v95
	ds_read_b128 v[34:37], v106 offset:7168
	ds_read_b128 v[38:41], v106 offset:19200
	ds_read_b128 v[42:45], v106 offset:19456
	ds_read_b128 v[46:49], v106 offset:19712
	v_pk_mul_f32 v[96:97], v[148:149], v[156:157] op_sel_hi:[1,0]
	v_pk_fma_f32 v[98:99], v[4:5], v[142:143], v[98:99]
	v_pk_mul_f32 v[100:101], v[148:149], v[158:159] op_sel_hi:[1,0]
	v_pk_fma_f32 v[102:103], v[8:9], v[142:143], v[102:103]
	ds_read_b128 v[50:53], v106 offset:6912
	v_pk_mul_f32 v[92:93], v[4:5], v[76:77]
	v_pk_mul_f32 v[94:95], v[8:9], v[76:77]
	v_add_f32_dpp v82, v82, v82 row_ror:1 row_mask:0xf bank_mask:0xf
	v_add_f32_dpp v84, v84, v84 row_ror:1 row_mask:0xf bank_mask:0xf
	ds_read_b32 v54, v107 offset:6912
	v_pk_fma_f32 v[96:97], v[2:3], v[140:141], v[96:97]
	v_pk_fma_f32 v[4:5], v[146:147], v[82:83], v[98:99] op_sel_hi:[1,0,1]
	v_pk_fma_f32 v[100:101], v[6:7], v[140:141], v[100:101]
	v_pk_fma_f32 v[8:9], v[146:147], v[84:85], v[102:103] op_sel_hi:[1,0,1]
	ds_read_b32 v56, v107 offset:6928
	v_pk_fma_f32 v[92:93], v[2:3], v[74:75], v[92:93]
	v_pk_fma_f32 v[94:95], v[6:7], v[74:75], v[94:95]
	s_waitcnt lgkmcnt(7)
	v_pk_fma_f32 v[2:3], v[144:145], v[82:83], v[96:97] op_sel_hi:[1,0,1]
	v_pk_fma_f32 v[6:7], v[144:145], v[84:85], v[100:101] op_sel_hi:[1,0,1]
	v_pk_mul_f32 v[86:87], v[4:5], v[12:13]
	v_pk_mul_f32 v[90:91], v[8:9], v[12:13]
	v_pk_fma_f32 v[86:87], v[2:3], v[10:11], v[86:87]
	v_pk_fma_f32 v[90:91], v[6:7], v[10:11], v[90:91]
	v_add_f32_e32 v82, v86, v87
	v_add_f32_e32 v84, v90, v91
	v_pk_mul_f32 v[98:99], v[24:25], v[30:31] op_sel_hi:[1,0]
	v_add_f32_dpp v82, v82, v82 row_ror:8 row_mask:0xf bank_mask:0xf
	v_add_f32_dpp v84, v84, v84 row_ror:8 row_mask:0xf bank_mask:0xf
	v_add_f32_e32 v166, v92, v93
	v_add_f32_dpp v82, v82, v82 row_ror:4 row_mask:0xf bank_mask:0xf
	v_add_f32_dpp v84, v84, v84 row_ror:4 row_mask:0xf bank_mask:0xf
	v_pk_mul_f32 v[102:103], v[24:25], v[32:33] op_sel_hi:[1,0]
	v_add_f32_dpp v82, v82, v82 row_ror:2 row_mask:0xf bank_mask:0xf
	v_add_f32_dpp v84, v84, v84 row_ror:2 row_mask:0xf bank_mask:0xf
	v_add_f32_e32 v196, v94, v95
	ds_read_b128 v[58:61], v106 offset:7936
	ds_read_b128 v[62:65], v106 offset:19968
	ds_read_b128 v[66:69], v106 offset:20224
	ds_read_b128 v[70:73], v106 offset:20480
	v_pk_mul_f32 v[96:97], v[22:23], v[30:31] op_sel_hi:[1,0]
	v_pk_fma_f32 v[98:99], v[4:5], v[16:17], v[98:99]
	v_pk_mul_f32 v[100:101], v[22:23], v[32:33] op_sel_hi:[1,0]
	v_pk_fma_f32 v[102:103], v[8:9], v[16:17], v[102:103]
	ds_read_b128 v[74:77], v106 offset:7680
	v_pk_mul_f32 v[92:93], v[4:5], v[154:155]
	v_pk_mul_f32 v[94:95], v[8:9], v[154:155]
	v_add_f32_dpp v82, v82, v82 row_ror:1 row_mask:0xf bank_mask:0xf
	v_add_f32_dpp v84, v84, v84 row_ror:1 row_mask:0xf bank_mask:0xf
	ds_read_b32 v78, v107 offset:7680
	v_pk_fma_f32 v[96:97], v[2:3], v[14:15], v[96:97]
	v_pk_fma_f32 v[4:5], v[20:21], v[82:83], v[98:99] op_sel_hi:[1,0,1]
	v_pk_fma_f32 v[100:101], v[6:7], v[14:15], v[100:101]
	v_pk_fma_f32 v[8:9], v[20:21], v[84:85], v[102:103] op_sel_hi:[1,0,1]
	ds_read_b32 v80, v107 offset:7696
	v_pk_fma_f32 v[92:93], v[2:3], v[152:153], v[92:93]
	v_pk_fma_f32 v[94:95], v[6:7], v[152:153], v[94:95]
	s_waitcnt lgkmcnt(7)
	v_pk_fma_f32 v[2:3], v[18:19], v[82:83], v[96:97] op_sel_hi:[1,0,1]
	v_pk_fma_f32 v[6:7], v[18:19], v[84:85], v[100:101] op_sel_hi:[1,0,1]
	v_pk_mul_f32 v[86:87], v[4:5], v[36:37]
	v_pk_mul_f32 v[90:91], v[8:9], v[36:37]
	v_pk_fma_f32 v[86:87], v[2:3], v[34:35], v[86:87]
	v_pk_fma_f32 v[90:91], v[6:7], v[34:35], v[90:91]
	v_add_f32_e32 v82, v86, v87
	v_add_f32_e32 v84, v90, v91
	v_pk_mul_f32 v[98:99], v[48:49], v[54:55] op_sel_hi:[1,0]
	v_add_f32_dpp v82, v82, v82 row_ror:8 row_mask:0xf bank_mask:0xf
	v_add_f32_dpp v84, v84, v84 row_ror:8 row_mask:0xf bank_mask:0xf
	v_add_f32_e32 v167, v92, v93
	v_add_f32_dpp v82, v82, v82 row_ror:4 row_mask:0xf bank_mask:0xf
	v_add_f32_dpp v84, v84, v84 row_ror:4 row_mask:0xf bank_mask:0xf
	v_pk_mul_f32 v[102:103], v[48:49], v[56:57] op_sel_hi:[1,0]
	v_add_f32_dpp v82, v82, v82 row_ror:2 row_mask:0xf bank_mask:0xf
	v_add_f32_dpp v84, v84, v84 row_ror:2 row_mask:0xf bank_mask:0xf
	v_add_f32_e32 v197, v94, v95
	ds_read_b128 v[136:139], v106 offset:8704
	ds_read_b128 v[140:143], v106 offset:20736
	ds_read_b128 v[144:147], v106 offset:20992
	ds_read_b128 v[148:151], v106 offset:21248
	v_pk_mul_f32 v[96:97], v[46:47], v[54:55] op_sel_hi:[1,0]
	v_pk_fma_f32 v[98:99], v[4:5], v[40:41], v[98:99]
	v_pk_mul_f32 v[100:101], v[46:47], v[56:57] op_sel_hi:[1,0]
	v_pk_fma_f32 v[102:103], v[8:9], v[40:41], v[102:103]
	ds_read_b128 v[152:155], v106 offset:8448
	v_pk_mul_f32 v[92:93], v[4:5], v[28:29]
	v_pk_mul_f32 v[94:95], v[8:9], v[28:29]
	v_add_f32_dpp v82, v82, v82 row_ror:1 row_mask:0xf bank_mask:0xf
	v_add_f32_dpp v84, v84, v84 row_ror:1 row_mask:0xf bank_mask:0xf
	ds_read_b32 v156, v107 offset:8448
	v_pk_fma_f32 v[96:97], v[2:3], v[38:39], v[96:97]
	v_pk_fma_f32 v[4:5], v[44:45], v[82:83], v[98:99] op_sel_hi:[1,0,1]
	v_pk_fma_f32 v[100:101], v[6:7], v[38:39], v[100:101]
	v_pk_fma_f32 v[8:9], v[44:45], v[84:85], v[102:103] op_sel_hi:[1,0,1]
	ds_read_b32 v158, v107 offset:8464
	v_pk_fma_f32 v[92:93], v[2:3], v[26:27], v[92:93]
	v_pk_fma_f32 v[94:95], v[6:7], v[26:27], v[94:95]
	s_waitcnt lgkmcnt(7)
	v_pk_fma_f32 v[2:3], v[42:43], v[82:83], v[96:97] op_sel_hi:[1,0,1]
	v_pk_fma_f32 v[6:7], v[42:43], v[84:85], v[100:101] op_sel_hi:[1,0,1]
	v_pk_mul_f32 v[86:87], v[4:5], v[60:61]
	v_pk_mul_f32 v[90:91], v[8:9], v[60:61]
	v_pk_fma_f32 v[86:87], v[2:3], v[58:59], v[86:87]
	v_pk_fma_f32 v[90:91], v[6:7], v[58:59], v[90:91]
	v_add_f32_e32 v82, v86, v87
	v_add_f32_e32 v84, v90, v91
	v_pk_mul_f32 v[98:99], v[72:73], v[78:79] op_sel_hi:[1,0]
	v_add_f32_dpp v82, v82, v82 row_ror:8 row_mask:0xf bank_mask:0xf
	v_add_f32_dpp v84, v84, v84 row_ror:8 row_mask:0xf bank_mask:0xf
	v_add_f32_e32 v168, v92, v93
	v_add_f32_dpp v82, v82, v82 row_ror:4 row_mask:0xf bank_mask:0xf
	v_add_f32_dpp v84, v84, v84 row_ror:4 row_mask:0xf bank_mask:0xf
	v_pk_mul_f32 v[102:103], v[72:73], v[80:81] op_sel_hi:[1,0]
	v_add_f32_dpp v82, v82, v82 row_ror:2 row_mask:0xf bank_mask:0xf
	v_add_f32_dpp v84, v84, v84 row_ror:2 row_mask:0xf bank_mask:0xf
	v_add_f32_e32 v198, v94, v95
	ds_read_b128 v[10:13], v106 offset:9472
	ds_read_b128 v[14:17], v106 offset:21504
	ds_read_b128 v[18:21], v106 offset:21760
	ds_read_b128 v[22:25], v106 offset:22016
	v_pk_mul_f32 v[96:97], v[70:71], v[78:79] op_sel_hi:[1,0]
	v_pk_fma_f32 v[98:99], v[4:5], v[64:65], v[98:99]
	v_pk_mul_f32 v[100:101], v[70:71], v[80:81] op_sel_hi:[1,0]
	v_pk_fma_f32 v[102:103], v[8:9], v[64:65], v[102:103]
	ds_read_b128 v[26:29], v106 offset:9216
	v_pk_mul_f32 v[92:93], v[4:5], v[52:53]
	v_pk_mul_f32 v[94:95], v[8:9], v[52:53]
	v_add_f32_dpp v82, v82, v82 row_ror:1 row_mask:0xf bank_mask:0xf
	v_add_f32_dpp v84, v84, v84 row_ror:1 row_mask:0xf bank_mask:0xf
	ds_read_b32 v30, v107 offset:9216
	v_pk_fma_f32 v[96:97], v[2:3], v[62:63], v[96:97]
	v_pk_fma_f32 v[4:5], v[68:69], v[82:83], v[98:99] op_sel_hi:[1,0,1]
	v_pk_fma_f32 v[100:101], v[6:7], v[62:63], v[100:101]
	v_pk_fma_f32 v[8:9], v[68:69], v[84:85], v[102:103] op_sel_hi:[1,0,1]
	ds_read_b32 v32, v107 offset:9232
	v_pk_fma_f32 v[92:93], v[2:3], v[50:51], v[92:93]
	v_pk_fma_f32 v[94:95], v[6:7], v[50:51], v[94:95]
	s_waitcnt lgkmcnt(7)
	v_pk_fma_f32 v[2:3], v[66:67], v[82:83], v[96:97] op_sel_hi:[1,0,1]
	v_pk_fma_f32 v[6:7], v[66:67], v[84:85], v[100:101] op_sel_hi:[1,0,1]
	v_pk_mul_f32 v[86:87], v[4:5], v[138:139]
	v_pk_mul_f32 v[90:91], v[8:9], v[138:139]
	v_pk_fma_f32 v[86:87], v[2:3], v[136:137], v[86:87]
	v_pk_fma_f32 v[90:91], v[6:7], v[136:137], v[90:91]
	v_add_f32_e32 v82, v86, v87
	v_add_f32_e32 v84, v90, v91
	v_pk_mul_f32 v[98:99], v[150:151], v[156:157] op_sel_hi:[1,0]
	v_add_f32_dpp v82, v82, v82 row_ror:8 row_mask:0xf bank_mask:0xf
	v_add_f32_dpp v84, v84, v84 row_ror:8 row_mask:0xf bank_mask:0xf
	v_add_f32_e32 v169, v92, v93
	v_add_f32_dpp v82, v82, v82 row_ror:4 row_mask:0xf bank_mask:0xf
	v_add_f32_dpp v84, v84, v84 row_ror:4 row_mask:0xf bank_mask:0xf
	v_pk_mul_f32 v[102:103], v[150:151], v[158:159] op_sel_hi:[1,0]
	v_add_f32_dpp v82, v82, v82 row_ror:2 row_mask:0xf bank_mask:0xf
	v_add_f32_dpp v84, v84, v84 row_ror:2 row_mask:0xf bank_mask:0xf
	v_add_f32_e32 v199, v94, v95
	ds_read_b128 v[34:37], v106 offset:10240
	ds_read_b128 v[38:41], v106 offset:22272
	ds_read_b128 v[42:45], v106 offset:22528
	ds_read_b128 v[46:49], v106 offset:22784
	v_pk_mul_f32 v[96:97], v[148:149], v[156:157] op_sel_hi:[1,0]
	v_pk_fma_f32 v[98:99], v[4:5], v[142:143], v[98:99]
	v_pk_mul_f32 v[100:101], v[148:149], v[158:159] op_sel_hi:[1,0]
	v_pk_fma_f32 v[102:103], v[8:9], v[142:143], v[102:103]
	ds_read_b128 v[50:53], v106 offset:9984
	v_pk_mul_f32 v[92:93], v[4:5], v[76:77]
	v_pk_mul_f32 v[94:95], v[8:9], v[76:77]
	v_add_f32_dpp v82, v82, v82 row_ror:1 row_mask:0xf bank_mask:0xf
	v_add_f32_dpp v84, v84, v84 row_ror:1 row_mask:0xf bank_mask:0xf
	ds_read_b32 v54, v107 offset:9984
	v_pk_fma_f32 v[96:97], v[2:3], v[140:141], v[96:97]
	v_pk_fma_f32 v[4:5], v[146:147], v[82:83], v[98:99] op_sel_hi:[1,0,1]
	v_pk_fma_f32 v[100:101], v[6:7], v[140:141], v[100:101]
	v_pk_fma_f32 v[8:9], v[146:147], v[84:85], v[102:103] op_sel_hi:[1,0,1]
	ds_read_b32 v56, v107 offset:10000
	v_pk_fma_f32 v[92:93], v[2:3], v[74:75], v[92:93]
	v_pk_fma_f32 v[94:95], v[6:7], v[74:75], v[94:95]
	s_waitcnt lgkmcnt(7)
	v_pk_fma_f32 v[2:3], v[144:145], v[82:83], v[96:97] op_sel_hi:[1,0,1]
	v_pk_fma_f32 v[6:7], v[144:145], v[84:85], v[100:101] op_sel_hi:[1,0,1]
	v_pk_mul_f32 v[86:87], v[4:5], v[12:13]
	v_pk_mul_f32 v[90:91], v[8:9], v[12:13]
	v_pk_fma_f32 v[86:87], v[2:3], v[10:11], v[86:87]
	v_pk_fma_f32 v[90:91], v[6:7], v[10:11], v[90:91]
	v_add_f32_e32 v82, v86, v87
	v_add_f32_e32 v84, v90, v91
	v_pk_mul_f32 v[98:99], v[24:25], v[30:31] op_sel_hi:[1,0]
	v_add_f32_dpp v82, v82, v82 row_ror:8 row_mask:0xf bank_mask:0xf
	v_add_f32_dpp v84, v84, v84 row_ror:8 row_mask:0xf bank_mask:0xf
	v_add_f32_e32 v170, v92, v93
	v_add_f32_dpp v82, v82, v82 row_ror:4 row_mask:0xf bank_mask:0xf
	v_add_f32_dpp v84, v84, v84 row_ror:4 row_mask:0xf bank_mask:0xf
	v_pk_mul_f32 v[102:103], v[24:25], v[32:33] op_sel_hi:[1,0]
	v_add_f32_dpp v82, v82, v82 row_ror:2 row_mask:0xf bank_mask:0xf
	v_add_f32_dpp v84, v84, v84 row_ror:2 row_mask:0xf bank_mask:0xf
	v_add_f32_e32 v200, v94, v95
	ds_read_b128 v[58:61], v106 offset:11008
	ds_read_b128 v[62:65], v106 offset:23040
	ds_read_b128 v[66:69], v106 offset:23296
	ds_read_b128 v[70:73], v106 offset:23552
	v_pk_mul_f32 v[96:97], v[22:23], v[30:31] op_sel_hi:[1,0]
	v_pk_fma_f32 v[98:99], v[4:5], v[16:17], v[98:99]
	v_pk_mul_f32 v[100:101], v[22:23], v[32:33] op_sel_hi:[1,0]
	v_pk_fma_f32 v[102:103], v[8:9], v[16:17], v[102:103]
	ds_read_b128 v[74:77], v106 offset:10752
	v_pk_mul_f32 v[92:93], v[4:5], v[154:155]
	v_pk_mul_f32 v[94:95], v[8:9], v[154:155]
	v_add_f32_dpp v82, v82, v82 row_ror:1 row_mask:0xf bank_mask:0xf
	v_add_f32_dpp v84, v84, v84 row_ror:1 row_mask:0xf bank_mask:0xf
	ds_read_b32 v78, v107 offset:10752
	v_pk_fma_f32 v[96:97], v[2:3], v[14:15], v[96:97]
	v_pk_fma_f32 v[4:5], v[20:21], v[82:83], v[98:99] op_sel_hi:[1,0,1]
	v_pk_fma_f32 v[100:101], v[6:7], v[14:15], v[100:101]
	v_pk_fma_f32 v[8:9], v[20:21], v[84:85], v[102:103] op_sel_hi:[1,0,1]
	ds_read_b32 v80, v107 offset:10768
	v_pk_fma_f32 v[92:93], v[2:3], v[152:153], v[92:93]
	v_pk_fma_f32 v[94:95], v[6:7], v[152:153], v[94:95]
	s_waitcnt lgkmcnt(7)
	v_pk_fma_f32 v[2:3], v[18:19], v[82:83], v[96:97] op_sel_hi:[1,0,1]
	v_pk_fma_f32 v[6:7], v[18:19], v[84:85], v[100:101] op_sel_hi:[1,0,1]
	v_pk_mul_f32 v[86:87], v[4:5], v[36:37]
	v_pk_mul_f32 v[90:91], v[8:9], v[36:37]
	v_pk_fma_f32 v[86:87], v[2:3], v[34:35], v[86:87]
	v_pk_fma_f32 v[90:91], v[6:7], v[34:35], v[90:91]
	v_add_f32_e32 v82, v86, v87
	v_add_f32_e32 v84, v90, v91
	v_pk_mul_f32 v[98:99], v[48:49], v[54:55] op_sel_hi:[1,0]
	v_add_f32_dpp v82, v82, v82 row_ror:8 row_mask:0xf bank_mask:0xf
	v_add_f32_dpp v84, v84, v84 row_ror:8 row_mask:0xf bank_mask:0xf
	v_add_f32_e32 v171, v92, v93
	v_add_f32_dpp v82, v82, v82 row_ror:4 row_mask:0xf bank_mask:0xf
	v_add_f32_dpp v84, v84, v84 row_ror:4 row_mask:0xf bank_mask:0xf
	v_pk_mul_f32 v[102:103], v[48:49], v[56:57] op_sel_hi:[1,0]
	v_add_f32_dpp v82, v82, v82 row_ror:2 row_mask:0xf bank_mask:0xf
	v_add_f32_dpp v84, v84, v84 row_ror:2 row_mask:0xf bank_mask:0xf
	v_add_f32_e32 v201, v94, v95
	ds_read_b128 v[136:139], v106 offset:11776
	ds_read_b128 v[140:143], v106 offset:23808
	ds_read_b128 v[144:147], v106 offset:24064
	ds_read_b128 v[148:151], v106 offset:24320
	v_pk_mul_f32 v[96:97], v[46:47], v[54:55] op_sel_hi:[1,0]
	v_pk_fma_f32 v[98:99], v[4:5], v[40:41], v[98:99]
	v_pk_mul_f32 v[100:101], v[46:47], v[56:57] op_sel_hi:[1,0]
	v_pk_fma_f32 v[102:103], v[8:9], v[40:41], v[102:103]
	ds_read_b128 v[152:155], v106 offset:11520
	v_pk_mul_f32 v[92:93], v[4:5], v[28:29]
	v_pk_mul_f32 v[94:95], v[8:9], v[28:29]
	v_add_f32_dpp v82, v82, v82 row_ror:1 row_mask:0xf bank_mask:0xf
	v_add_f32_dpp v84, v84, v84 row_ror:1 row_mask:0xf bank_mask:0xf
	ds_read_b32 v156, v107 offset:11520
	v_pk_fma_f32 v[96:97], v[2:3], v[38:39], v[96:97]
	v_pk_fma_f32 v[4:5], v[44:45], v[82:83], v[98:99] op_sel_hi:[1,0,1]
	v_pk_fma_f32 v[100:101], v[6:7], v[38:39], v[100:101]
	v_pk_fma_f32 v[8:9], v[44:45], v[84:85], v[102:103] op_sel_hi:[1,0,1]
	ds_read_b32 v158, v107 offset:11536
	v_pk_fma_f32 v[92:93], v[2:3], v[26:27], v[92:93]
	v_pk_fma_f32 v[94:95], v[6:7], v[26:27], v[94:95]
	s_waitcnt lgkmcnt(7)
	v_pk_fma_f32 v[2:3], v[42:43], v[82:83], v[96:97] op_sel_hi:[1,0,1]
	v_pk_fma_f32 v[6:7], v[42:43], v[84:85], v[100:101] op_sel_hi:[1,0,1]
	v_pk_mul_f32 v[86:87], v[4:5], v[60:61]
	v_pk_mul_f32 v[90:91], v[8:9], v[60:61]
	v_pk_fma_f32 v[86:87], v[2:3], v[58:59], v[86:87]
	v_pk_fma_f32 v[90:91], v[6:7], v[58:59], v[90:91]
	v_add_f32_e32 v82, v86, v87
	v_add_f32_e32 v84, v90, v91
	v_pk_mul_f32 v[98:99], v[72:73], v[78:79] op_sel_hi:[1,0]
	v_add_f32_dpp v82, v82, v82 row_ror:8 row_mask:0xf bank_mask:0xf
	v_add_f32_dpp v84, v84, v84 row_ror:8 row_mask:0xf bank_mask:0xf
	v_add_f32_e32 v172, v92, v93
	v_add_f32_dpp v82, v82, v82 row_ror:4 row_mask:0xf bank_mask:0xf
	v_add_f32_dpp v84, v84, v84 row_ror:4 row_mask:0xf bank_mask:0xf
	v_pk_mul_f32 v[102:103], v[72:73], v[80:81] op_sel_hi:[1,0]
	v_add_f32_dpp v82, v82, v82 row_ror:2 row_mask:0xf bank_mask:0xf
	v_add_f32_dpp v84, v84, v84 row_ror:2 row_mask:0xf bank_mask:0xf
	v_add_f32_e32 v202, v94, v95
	ds_read_b128 v[10:13], v108 offset:256
	ds_read_b128 v[14:17], v108 offset:12288
	ds_read_b128 v[18:21], v108 offset:12544
	ds_read_b128 v[22:25], v108 offset:12800
	v_pk_mul_f32 v[96:97], v[70:71], v[78:79] op_sel_hi:[1,0]
	v_pk_fma_f32 v[98:99], v[4:5], v[64:65], v[98:99]
	v_pk_mul_f32 v[100:101], v[70:71], v[80:81] op_sel_hi:[1,0]
	v_pk_fma_f32 v[102:103], v[8:9], v[64:65], v[102:103]
	ds_read_b128 v[26:29], v108 offset:0
	v_pk_mul_f32 v[92:93], v[4:5], v[52:53]
	v_pk_mul_f32 v[94:95], v[8:9], v[52:53]
	v_add_f32_dpp v82, v82, v82 row_ror:1 row_mask:0xf bank_mask:0xf
	v_add_f32_dpp v84, v84, v84 row_ror:1 row_mask:0xf bank_mask:0xf
	ds_read_b32 v30, v109 offset:0
	v_pk_fma_f32 v[96:97], v[2:3], v[62:63], v[96:97]
	v_pk_fma_f32 v[4:5], v[68:69], v[82:83], v[98:99] op_sel_hi:[1,0,1]
	v_pk_fma_f32 v[100:101], v[6:7], v[62:63], v[100:101]
	v_pk_fma_f32 v[8:9], v[68:69], v[84:85], v[102:103] op_sel_hi:[1,0,1]
	ds_read_b32 v32, v109 offset:16
	v_pk_fma_f32 v[92:93], v[2:3], v[50:51], v[92:93]
	v_pk_fma_f32 v[94:95], v[6:7], v[50:51], v[94:95]
	s_waitcnt lgkmcnt(7)
	v_pk_fma_f32 v[2:3], v[66:67], v[82:83], v[96:97] op_sel_hi:[1,0,1]
	v_pk_fma_f32 v[6:7], v[66:67], v[84:85], v[100:101] op_sel_hi:[1,0,1]
	v_pk_mul_f32 v[86:87], v[4:5], v[138:139]
	v_pk_mul_f32 v[90:91], v[8:9], v[138:139]
	v_pk_fma_f32 v[86:87], v[2:3], v[136:137], v[86:87]
	v_pk_fma_f32 v[90:91], v[6:7], v[136:137], v[90:91]
	v_add_f32_e32 v82, v86, v87
	v_add_f32_e32 v84, v90, v91
	v_add_f32_e32 v173, v92, v93
	v_add_f32_dpp v82, v82, v82 row_ror:8 row_mask:0xf bank_mask:0xf
	v_add_f32_dpp v84, v84, v84 row_ror:8 row_mask:0xf bank_mask:0xf
	v_add_f32_e32 v203, v94, v95
	v_add_f32_dpp v82, v82, v82 row_ror:4 row_mask:0xf bank_mask:0xf
	v_add_f32_dpp v84, v84, v84 row_ror:4 row_mask:0xf bank_mask:0xf
	v_pk_mul_f32 v[98:99], v[150:151], v[156:157] op_sel_hi:[1,0]
	v_add_f32_dpp v82, v82, v82 row_ror:2 row_mask:0xf bank_mask:0xf
	v_add_f32_dpp v84, v84, v84 row_ror:2 row_mask:0xf bank_mask:0xf
	v_pk_mul_f32 v[102:103], v[150:151], v[158:159] op_sel_hi:[1,0]
	v_pk_mul_f32 v[92:93], v[4:5], v[76:77]
	v_pk_mul_f32 v[94:95], v[8:9], v[76:77]
	v_pk_mul_f32 v[96:97], v[148:149], v[156:157] op_sel_hi:[1,0]
	v_pk_fma_f32 v[98:99], v[4:5], v[142:143], v[98:99]
	v_pk_mul_f32 v[100:101], v[148:149], v[158:159] op_sel_hi:[1,0]
	v_pk_fma_f32 v[102:103], v[8:9], v[142:143], v[102:103]
	v_pk_fma_f32 v[92:93], v[2:3], v[74:75], v[92:93]
	v_pk_fma_f32 v[94:95], v[6:7], v[74:75], v[94:95]
	v_add_f32_dpp v82, v82, v82 row_ror:1 row_mask:0xf bank_mask:0xf
	v_add_f32_dpp v84, v84, v84 row_ror:1 row_mask:0xf bank_mask:0xf
	v_pk_fma_f32 v[96:97], v[2:3], v[140:141], v[96:97]
	v_pk_fma_f32 v[4:5], v[146:147], v[82:83], v[98:99] op_sel_hi:[1,0,1]
	v_pk_fma_f32 v[100:101], v[6:7], v[140:141], v[100:101]
	v_pk_fma_f32 v[8:9], v[146:147], v[84:85], v[102:103] op_sel_hi:[1,0,1]
	v_add_f32_e32 v174, v92, v93
	v_add_f32_e32 v204, v94, v95
	v_pk_fma_f32 v[2:3], v[144:145], v[82:83], v[96:97] op_sel_hi:[1,0,1]
	v_pk_fma_f32 v[6:7], v[144:145], v[84:85], v[100:101] op_sel_hi:[1,0,1]
	v_pk_mul_f32 v[92:93], v[4:5], v[154:155]
	v_pk_mul_f32 v[94:95], v[8:9], v[154:155]
	v_pk_fma_f32 v[92:93], v[2:3], v[152:153], v[92:93]
	v_pk_fma_f32 v[94:95], v[6:7], v[152:153], v[94:95]
	v_add_f32_e32 v175, v92, v93
	v_add_f32_e32 v205, v94, v95
	v_add_f32_dpp v160, v160, v160 row_mirror row_mask:0xf bank_mask:0x3
	v_add_f32_dpp v161, v161, v161 row_mirror row_mask:0xf bank_mask:0x3
	v_add_f32_dpp v162, v162, v162 row_mirror row_mask:0xf bank_mask:0x3
	v_add_f32_dpp v163, v163, v163 row_mirror row_mask:0xf bank_mask:0x3
	v_add_f32_dpp v190, v190, v190 row_mirror row_mask:0xf bank_mask:0x3
	v_add_f32_dpp v191, v191, v191 row_mirror row_mask:0xf bank_mask:0x3
	v_add_f32_dpp v192, v192, v192 row_mirror row_mask:0xf bank_mask:0x3
	v_add_f32_dpp v193, v193, v193 row_mirror row_mask:0xf bank_mask:0x3
	v_add_f32_dpp v160, v168, v168 row_mirror row_mask:0xf bank_mask:0xc
	v_add_f32_dpp v161, v169, v169 row_mirror row_mask:0xf bank_mask:0xc
	v_add_f32_dpp v162, v170, v170 row_mirror row_mask:0xf bank_mask:0xc
	v_add_f32_dpp v163, v171, v171 row_mirror row_mask:0xf bank_mask:0xc
	v_add_f32_dpp v164, v164, v164 row_mirror row_mask:0xf bank_mask:0x3
	v_add_f32_dpp v165, v165, v165 row_mirror row_mask:0xf bank_mask:0x3
	v_add_f32_dpp v166, v166, v166 row_mirror row_mask:0xf bank_mask:0x3
	v_add_f32_dpp v167, v167, v167 row_mirror row_mask:0xf bank_mask:0x3
	v_add_f32_dpp v190, v198, v198 row_mirror row_mask:0xf bank_mask:0xc
	v_add_f32_dpp v191, v199, v199 row_mirror row_mask:0xf bank_mask:0xc
	v_add_f32_dpp v192, v200, v200 row_mirror row_mask:0xf bank_mask:0xc
	v_add_f32_dpp v193, v201, v201 row_mirror row_mask:0xf bank_mask:0xc
	v_add_f32_dpp v194, v194, v194 row_mirror row_mask:0xf bank_mask:0x3
	v_add_f32_dpp v195, v195, v195 row_mirror row_mask:0xf bank_mask:0x3
	v_add_f32_dpp v196, v196, v196 row_mirror row_mask:0xf bank_mask:0x3
	v_add_f32_dpp v197, v197, v197 row_mirror row_mask:0xf bank_mask:0x3
	v_add_f32_dpp v164, v172, v172 row_mirror row_mask:0xf bank_mask:0xc
	v_add_f32_dpp v165, v173, v173 row_mirror row_mask:0xf bank_mask:0xc
	v_add_f32_dpp v166, v174, v174 row_mirror row_mask:0xf bank_mask:0xc
	v_add_f32_dpp v167, v175, v175 row_mirror row_mask:0xf bank_mask:0xc
	v_add_f32_dpp v194, v202, v202 row_mirror row_mask:0xf bank_mask:0xc
	v_add_f32_dpp v195, v203, v203 row_mirror row_mask:0xf bank_mask:0xc
	v_add_f32_dpp v196, v204, v204 row_mirror row_mask:0xf bank_mask:0xc
	v_add_f32_dpp v197, v205, v205 row_mirror row_mask:0xf bank_mask:0xc
	v_add_f32_dpp v160, v160, v160 row_half_mirror row_mask:0xf bank_mask:0x5
	v_add_f32_dpp v161, v161, v161 row_half_mirror row_mask:0xf bank_mask:0x5
	v_add_f32_dpp v162, v162, v162 row_half_mirror row_mask:0xf bank_mask:0x5
	v_add_f32_dpp v163, v163, v163 row_half_mirror row_mask:0xf bank_mask:0x5
	v_add_f32_dpp v190, v190, v190 row_half_mirror row_mask:0xf bank_mask:0x5
	v_add_f32_dpp v191, v191, v191 row_half_mirror row_mask:0xf bank_mask:0x5
	v_add_f32_dpp v160, v164, v164 row_half_mirror row_mask:0xf bank_mask:0xa
	v_add_f32_dpp v161, v165, v165 row_half_mirror row_mask:0xf bank_mask:0xa
	v_add_f32_dpp v162, v166, v166 row_half_mirror row_mask:0xf bank_mask:0xa
	v_add_f32_dpp v163, v167, v167 row_half_mirror row_mask:0xf bank_mask:0xa
	v_add_f32_dpp v190, v194, v194 row_half_mirror row_mask:0xf bank_mask:0xa
	v_cndmask_b32_e64 v169, v162, v160, s[10:11]
	v_cndmask_b32_e64 v171, v163, v161, s[10:11]
	ds_read_b128 v[34:37], v108 offset:1024
	v_add_f32_dpp v191, v195, v195 row_half_mirror row_mask:0xf bank_mask:0xa
	ds_read_b128 v[38:41], v108 offset:13056
	v_add_f32_dpp v192, v192, v192 row_half_mirror row_mask:0xf bank_mask:0x5
	v_cndmask_b32_e64 v168, v160, v162, s[10:11]
	v_cndmask_b32_e64 v170, v161, v163, s[10:11]
	ds_read_b128 v[42:45], v108 offset:13312
	v_add_f32_dpp v192, v196, v196 row_half_mirror row_mask:0xf bank_mask:0xa
	v_add_f32_dpp v168, v169, v168 quad_perm:[2,3,0,1] row_mask:0xf bank_mask:0xf
	v_add_f32_dpp v170, v171, v170 quad_perm:[2,3,0,1] row_mask:0xf bank_mask:0xf
	ds_read_b128 v[46:49], v108 offset:13568
	v_add_f32_dpp v193, v193, v193 row_half_mirror row_mask:0xf bank_mask:0x5
	v_cndmask_b32_e64 v169, v170, v168, s[14:15]
	ds_read_b128 v[50:53], v108 offset:768
	v_add_f32_dpp v193, v197, v197 row_half_mirror row_mask:0xf bank_mask:0xa
	ds_read_b32 v54, v109 offset:768
	v_cndmask_b32_e64 v198, v190, v192, s[10:11]
	v_cndmask_b32_e64 v171, v168, v170, s[14:15]
	ds_read_b32 v56, v109 offset:784
	v_cndmask_b32_e64 v199, v192, v190, s[10:11]
	v_cndmask_b32_e64 v201, v193, v191, s[10:11]
	v_cndmask_b32_e64 v200, v191, v193, s[10:11]
	v_add_f32_dpp v198, v199, v198 quad_perm:[2,3,0,1] row_mask:0xf bank_mask:0xf
	v_add_f32_dpp v200, v201, v200 quad_perm:[2,3,0,1] row_mask:0xf bank_mask:0xf
	v_cndmask_b32_e64 v199, v200, v198, s[14:15]
	v_cndmask_b32_e64 v201, v198, v200, s[14:15]
	v_add_f32_dpp v171, v169, v171 quad_perm:[1,0,3,2] row_mask:0xf bank_mask:0xf
	v_add_f32_dpp v201, v199, v201 quad_perm:[1,0,3,2] row_mask:0xf bank_mask:0xf
	s_mov_b32 s8, s20
	v_mov_b32_e32 v106, v108
	v_mov_b32_e32 v107, v109
	global_store_dword v113, v171, s[4:5]
	global_store_dword v113, v201, s[4:5] offset:16
	s_add_u32 s4, s4, s6
	s_addc_u32 s5, s5, s7
	s_sub_u32 s1, s1, 1
	s_cmp_lg_u32 s1, 0
	s_cbranch_scc1 .Lsc_c_loop
	s_cmp_lt_u32 s71, 64
	s_cbranch_scc1 .Lsc_c_end
	v_readlane_b32 s4, v253, 49
	v_readlane_b32 s5, v253, 50
	s_nop 3
	s_add_u32 s4, s4, s9
	s_addc_u32 s5, s5, 0
	s_nop 3
	global_store_dwordx4 v114, v[2:5], s[4:5]
	global_store_dwordx4 v114, v[6:9], s[4:5] offset:1024
.Lsc_c_end:
	s_waitcnt lgkmcnt(0)
	s_barrier
	s_branch .Lsc_next
.Lsc_loader:
	s_sub_u32 s11, s0, 4
	s_mul_i32 s22, s22, 0x300
	s_cmp_lt_u32 s11, 2
	s_cbranch_scc1 .Lsc_ld_recs
	v_readlane_b32 s4, v253, 30
	v_readlane_b32 s5, v253, 31
	s_mul_i32 s1, s24, 0x1800000
	s_add_u32 s22, s22, s1
	s_branch .Lsc_ld_base

.Lsc_ld_base:
	s_nop 0
	s_add_u32 s4, s4, s22
	s_addc_u32 s5, s5, 0
	s_cmp_eq_u32 s24, 0
	s_cbranch_scc1 .Lsc_ld_fwd
	s_sub_u32 s1, s23, 1
	s_mul_i32 s1, s1, 0x3000
	s_add_u32 s4, s4, s1
	s_addc_u32 s5, s5, 0
	s_mov_b32 s6, 0xffffd000
	s_mov_b32 s7, -1
	s_branch .Lsc_ld_dirdone

.Lsc_ld_dirdone:
	v_and_b32_e32 v8, 63, v0
	s_and_b32 s1, s11, 1
	v_lshlrev_b32_e32 v8, 4, v8
	s_mul_i32 s1, s1, 0x1800
	s_nop 0
	v_add_u32_e32 v8, s1, v8
	v_mov_b32_e32 v9, v8
	v_lshrrev_b32_e32 v10, 8, v9
	v_mul_u32_u24_e32 v10, 0xaaab, v10
	v_lshrrev_b32_e32 v10, 17, v10
	v_mul_u32_u24_e32 v11, 0x600, v10
	v_sub_u32_e32 v11, 0x2d00, v11
	v_mul_lo_u32 v11, v11, s24
	v_add_u32_e32 v2, v9, v11
	v_add_u32_e32 v9, 0x400, v8
	v_lshrrev_b32_e32 v10, 8, v9
	v_mul_u32_u24_e32 v10, 0xaaab, v10
	v_lshrrev_b32_e32 v10, 17, v10
	v_mul_u32_u24_e32 v11, 0x600, v10
	v_sub_u32_e32 v11, 0x2d00, v11
	v_mul_lo_u32 v11, v11, s24
	v_add_u32_e32 v3, v9, v11
	v_add_u32_e32 v9, 0x800, v8
	v_lshrrev_b32_e32 v10, 8, v9
	v_mul_u32_u24_e32 v10, 0xaaab, v10
	v_lshrrev_b32_e32 v10, 17, v10
	v_mul_u32_u24_e32 v11, 0x600, v10
	v_sub_u32_e32 v11, 0x2d00, v11
	v_mul_lo_u32 v11, v11, s24
	v_add_u32_e32 v4, v9, v11
	v_add_u32_e32 v9, 0xc00, v8
	v_lshrrev_b32_e32 v10, 8, v9
	v_mul_u32_u24_e32 v10, 0xaaab, v10
	v_lshrrev_b32_e32 v10, 17, v10
	v_mul_u32_u24_e32 v11, 0x600, v10
	v_sub_u32_e32 v11, 0x2d00, v11
	v_mul_lo_u32 v11, v11, s24
	v_add_u32_e32 v5, v9, v11
	v_add_u32_e32 v9, 0x1000, v8
	v_lshrrev_b32_e32 v10, 8, v9
	v_mul_u32_u24_e32 v10, 0xaaab, v10
	v_lshrrev_b32_e32 v10, 17, v10
	v_mul_u32_u24_e32 v11, 0x600, v10
	v_sub_u32_e32 v11, 0x2d00, v11
	v_mul_lo_u32 v11, v11, s24
	v_add_u32_e32 v6, v9, v11
	v_add_u32_e32 v9, 0x1400, v8
	v_lshrrev_b32_e32 v10, 8, v9
	v_mul_u32_u24_e32 v10, 0xaaab, v10
	v_lshrrev_b32_e32 v10, 17, v10
	v_mul_u32_u24_e32 v11, 0x600, v10
	v_sub_u32_e32 v11, 0x2d00, v11
	v_mul_lo_u32 v11, v11, s24
	v_add_u32_e32 v7, v9, v11
	s_mul_i32 s8, s11, 0x1800
	s_add_u32 s8, s8, 0xf0
	s_mov_b32 s9, 0
	s_mov_b32 s10, 0
	s_sub_u32 s21, s23, 1
	s_mov_b32 m0, s8
	s_nop 0
	global_load_lds_dwordx4 v2, s[4:5]
	s_add_u32 m0, s8, 0x400
	s_nop 0
	global_load_lds_dwordx4 v3, s[4:5]
	s_add_u32 m0, s8, 0x800
	s_nop 0
	global_load_lds_dwordx4 v4, s[4:5]
	s_add_u32 m0, s8, 0xc00
	s_nop 0
	global_load_lds_dwordx4 v5, s[4:5]
	s_add_u32 m0, s8, 0x1000
	s_nop 0
	global_load_lds_dwordx4 v6, s[4:5]
	s_add_u32 m0, s8, 0x1400
	s_nop 0
	global_load_lds_dwordx4 v7, s[4:5]
	s_cmp_lt_u32 s10, s21
	s_cselect_b32 s1, s6, 0
	s_cselect_b32 s14, s7, 0
	s_cselect_b32 s15, 1, 0
	s_add_u32 s4, s4, s1
	s_addc_u32 s5, s5, s14
	s_add_u32 s10, s10, s15
	s_add_u32 s9, s9, 1
	s_add_u32 s8, s8, 0x6000
	s_cmp_eq_u32 s9, 5
	s_cselect_b32 s1, 0x1e000, 0
	s_cselect_b32 s9, 0, s9
	s_sub_u32 s8, s8, s1
	s_mov_b32 m0, s8
	s_nop 0
	global_load_lds_dwordx4 v2, s[4:5]
	s_add_u32 m0, s8, 0x400
	s_nop 0
	global_load_lds_dwordx4 v3, s[4:5]
	s_add_u32 m0, s8, 0x800
	s_nop 0
	global_load_lds_dwordx4 v4, s[4:5]
	s_add_u32 m0, s8, 0xc00
	s_nop 0
	global_load_lds_dwordx4 v5, s[4:5]
	s_add_u32 m0, s8, 0x1000
	s_nop 0
	global_load_lds_dwordx4 v6, s[4:5]
	s_add_u32 m0, s8, 0x1400
	s_nop 0
	global_load_lds_dwordx4 v7, s[4:5]
	s_cmp_lt_u32 s10, s21
	s_cselect_b32 s1, s6, 0
	s_cselect_b32 s14, s7, 0
	s_cselect_b32 s15, 1, 0
	s_add_u32 s4, s4, s1
	s_addc_u32 s5, s5, s14
	s_add_u32 s10, s10, s15
	s_add_u32 s9, s9, 1
	s_add_u32 s8, s8, 0x6000
	s_cmp_eq_u32 s9, 5
	s_cselect_b32 s1, 0x1e000, 0
	s_cselect_b32 s9, 0, s9
	s_sub_u32 s8, s8, s1
	s_mov_b32 m0, s8
	s_nop 0
	global_load_lds_dwordx4 v2, s[4:5]
	s_add_u32 m0, s8, 0x400
	s_nop 0
	global_load_lds_dwordx4 v3, s[4:5]
	s_add_u32 m0, s8, 0x800
	s_nop 0
	global_load_lds_dwordx4 v4, s[4:5]
	s_add_u32 m0, s8, 0xc00
	s_nop 0
	global_load_lds_dwordx4 v5, s[4:5]
	s_add_u32 m0, s8, 0x1000
	s_nop 0
	global_load_lds_dwordx4 v6, s[4:5]
	s_add_u32 m0, s8, 0x1400
	s_nop 0
	global_load_lds_dwordx4 v7, s[4:5]
	s_cmp_lt_u32 s10, s21
	s_cselect_b32 s1, s6, 0
	s_cselect_b32 s14, s7, 0
	s_cselect_b32 s15, 1, 0
	s_add_u32 s4, s4, s1
	s_addc_u32 s5, s5, s14
	s_add_u32 s10, s10, s15
	s_add_u32 s9, s9, 1
	s_add_u32 s8, s8, 0x6000
	s_cmp_eq_u32 s9, 5
	s_cselect_b32 s1, 0x1e000, 0
	s_cselect_b32 s9, 0, s9
	s_sub_u32 s8, s8, s1
	s_mov_b32 m0, s8
	s_nop 0
	global_load_lds_dwordx4 v2, s[4:5]
	s_add_u32 m0, s8, 0x400
	s_nop 0
	global_load_lds_dwordx4 v3, s[4:5]
	s_add_u32 m0, s8, 0x800
	s_nop 0
	global_load_lds_dwordx4 v4, s[4:5]
	s_add_u32 m0, s8, 0xc00
	s_nop 0
	global_load_lds_dwordx4 v5, s[4:5]
	s_add_u32 m0, s8, 0x1000
	s_nop 0
	global_load_lds_dwordx4 v6, s[4:5]
	s_add_u32 m0, s8, 0x1400
	s_nop 0
	global_load_lds_dwordx4 v7, s[4:5]
	s_cmp_lt_u32 s10, s21
	s_cselect_b32 s1, s6, 0
	s_cselect_b32 s14, s7, 0
	s_cselect_b32 s15, 1, 0
	s_add_u32 s4, s4, s1
	s_addc_u32 s5, s5, s14
	s_add_u32 s10, s10, s15
	s_add_u32 s9, s9, 1
	s_add_u32 s8, s8, 0x6000
	s_cmp_eq_u32 s9, 5
	s_cselect_b32 s1, 0x1e000, 0
	s_cselect_b32 s9, 0, s9
	s_sub_u32 s8, s8, s1
	s_waitcnt vmcnt(12)
	s_barrier
	s_mov_b32 s1, s23
.Lsc_ld_loop:
	s_waitcnt vmcnt(12)
	s_barrier
	s_mov_b32 s22, s1
	s_mov_b32 m0, s8
	s_nop 0
	global_load_lds_dwordx4 v2, s[4:5]
	s_add_u32 m0, s8, 0x400
	s_nop 0
	global_load_lds_dwordx4 v3, s[4:5]
	s_add_u32 m0, s8, 0x800
	s_nop 0
	global_load_lds_dwordx4 v4, s[4:5]
	s_add_u32 m0, s8, 0xc00
	s_nop 0
	global_load_lds_dwordx4 v5, s[4:5]
	s_add_u32 m0, s8, 0x1000
	s_nop 0
	global_load_lds_dwordx4 v6, s[4:5]
	s_add_u32 m0, s8, 0x1400
	s_nop 0
	global_load_lds_dwordx4 v7, s[4:5]
	s_cmp_lt_u32 s10, s21
	s_cselect_b32 s1, s6, 0
	s_cselect_b32 s14, s7, 0
	s_cselect_b32 s15, 1, 0
	s_add_u32 s4, s4, s1
	s_addc_u32 s5, s5, s14
	s_add_u32 s10, s10, s15
	s_add_u32 s9, s9, 1
	s_add_u32 s8, s8, 0x6000
	s_cmp_eq_u32 s9, 5
	s_cselect_b32 s1, 0x1e000, 0
	s_cselect_b32 s9, 0, s9
	s_sub_u32 s8, s8, s1
	s_sub_u32 s1, s22, 1
	s_cmp_lg_u32 s1, 0
	s_cbranch_scc1 .Lsc_ld_loop
	s_waitcnt vmcnt(0)
	s_barrier
.Lsc_next:
	s_add_u32 s25, s25, 1
	s_mul_i32 s1, s25, s70
	s_sub_u32 s4, s70, 1
	s_sub_u32 s4, s4, s2
	s_bitcmp1_b32 s25, 0
	s_cselect_b32 s4, s4, s2
	s_add_u32 s71, s1, s4
	s_branch .Lsc_task_loop

.LBB0_904:
	s_or_b64 exec, exec, s[0:1]
	s_ashr_i32 s20, s15, 5
	s_ashr_i32 s15, s14, 31
	v_mov_b32_e32 v43, v0
	s_barrier
	s_lshl_b64 s[0:1], s[14:15], 19
	v_readlane_b32 s8, v253, 28
	v_readlane_b32 s9, v253, 29
	v_ashrrev_i32_e32 v38, 3, v43
	s_add_u32 s8, s8, s0
	v_ashrrev_i32_e32 v39, 31, v38
	s_waitcnt vmcnt(0) lgkmcnt(0)
	v_lshlrev_b32_e32 v4, 3, v43
	s_addc_u32 s9, s9, s1
	v_lshlrev_b64 v[40:41], 11, v[38:39]
	v_and_b32_e32 v42, 56, v4
	v_lshl_add_u64 v[2:3], s[8:9], 0, v[40:41]
	v_lshlrev_b32_e32 v130, 1, v42
	v_lshl_add_u64 v[2:3], v[2:3], 0, v[130:131]
	s_mov_b32 s8, 0x20000
	v_add_co_u32_e32 v6, vcc, s8, v2
	s_ashr_i32 s21, s20, 31
	s_nop 0
	v_addc_co_u32_e32 v7, vcc, 0, v3, vcc
	s_mov_b32 s9, 0x40000
	s_lshl_b64 s[22:23], s[20:21], 18
	s_barrier
	global_load_dwordx4 v[14:17], v[2:3], off
	global_load_dwordx4 v[18:21], v[6:7], off
	v_add_co_u32_e32 v6, vcc, s9, v2
	s_add_u32 s54, s24, s22
	s_nop 0
	v_addc_co_u32_e32 v7, vcc, 0, v3, vcc
	s_mov_b32 s9, 0x60000
	s_addc_u32 s55, s25, s23
	v_add_co_u32_e32 v2, vcc, s9, v2
	v_lshl_add_u64 v[4:5], s[54:55], 0, v[40:41]
	s_nop 0
	v_addc_co_u32_e32 v3, vcc, 0, v3, vcc
	global_load_dwordx4 v[22:25], v[6:7], off
	global_load_dwordx4 v[26:29], v[2:3], off
	v_lshl_add_u64 v[2:3], v[4:5], 0, v[130:131]
	v_add_co_u32_e32 v4, vcc, s8, v2
	v_and_b32_e32 v39, 15, v43
	s_nop 0
	v_addc_co_u32_e32 v5, vcc, 0, v3, vcc
	global_load_dwordx4 v[30:33], v[2:3], off
	global_load_dwordx4 v[34:37], v[4:5], off
	v_lshrrev_b32_e32 v44, 1, v43
	v_and_b32_e32 v45, 0x4f, v43
	v_lshlrev_b32_e32 v43, 4, v43
	s_mov_b32 s54, 0x1fffffc0
	v_and_b32_e32 v43, 0x70, v43
	s_movk_i32 s84, 0x48
	v_and_or_b32 v46, v44, s54, v39
	v_mad_u64_u32 v[38:39], s[54:55], v38, s84, v[42:43]
	v_and_b32_e32 v44, 24, v44
	v_mul_lo_u32 v39, v46, s84
	v_lshl_add_u32 v86, v38, 1, v212
	v_add_lshl_u32 v84, v39, v44, 1
	v_lshl_add_u64 v[38:39], s[0:1], 0, v[40:41]
	v_lshl_add_u64 v[40:41], s[22:23], 0, v[40:41]
	v_mov_b32_e32 v2, 0
	v_mul_u32_u24_e32 v45, 0x48, v45
	v_or_b32_e32 v38, v38, v43
	v_or_b32_e32 v40, v40, v43
	s_mov_b32 s15, 0
	s_mov_b64 s[8:9], 0
	v_mov_b32_e32 v3, v2
	v_mov_b32_e32 v4, v2
	v_mov_b32_e32 v5, v2
	v_mov_b32_e32 v6, v2
	v_mov_b32_e32 v7, v2
	v_mov_b32_e32 v8, v2
	v_mov_b32_e32 v9, v2
	v_mov_b32_e32 v10, v2
	v_mov_b32_e32 v11, v2
	v_mov_b32_e32 v12, v2
	v_mov_b32_e32 v13, v2
	v_add_lshl_u32 v85, v45, v44, 1
	v_lshl_add_u64 v[80:81], s[18:19], 0, v[38:39]
	v_lshl_add_u64 v[82:83], s[12:13], 0, v[40:41]
	s_mov_b32 vcc_hi, 0
	s_mov_b32 vcc_lo, 0x88a3000
	v_lshl_add_u64 v[228:229], v[80:81], 0, vcc
	s_mov_b32 vcc_lo, 0x88c3000
	v_lshl_add_u64 v[230:231], v[80:81], 0, vcc
	s_mov_b32 vcc_lo, 0x88e3000
	v_lshl_add_u64 v[232:233], v[80:81], 0, vcc
	s_mov_b32 vcc_lo, 0x8903000
	v_lshl_add_u64 v[234:235], v[80:81], 0, vcc
	s_mov_b32 vcc_lo, 0x2080000
	v_lshl_add_u64 v[236:237], v[82:83], 0, vcc
	s_mov_b32 vcc_lo, 0x20a0000
	v_lshl_add_u64 v[238:239], v[82:83], 0, vcc
	global_load_dwordx4 v[172:175], v[228:229], off offset:1920
	global_load_dwordx4 v[176:179], v[230:231], off offset:1920
	global_load_dwordx4 v[180:183], v[232:233], off offset:1920
	global_load_dwordx4 v[184:187], v[234:235], off offset:1920
	global_load_dwordx4 v[188:191], v[236:237], off offset:128
	global_load_dwordx4 v[192:195], v[238:239], off offset:128
	v_mov_b32_e32 v38, v2
	v_mov_b32_e32 v39, v2
	v_mov_b32_e32 v40, v2
	v_mov_b32_e32 v41, v2
	v_mov_b32_e32 v42, v2
	v_mov_b32_e32 v43, v2
	v_mov_b32_e32 v44, v2
	s_waitcnt vmcnt(11)
	ds_write_b128 v86, v[14:17]
	s_waitcnt vmcnt(10)
	ds_write_b128 v86, v[18:21] offset:9216
	s_waitcnt vmcnt(9)
	ds_write_b128 v86, v[22:25] offset:18432
	s_waitcnt vmcnt(8)
	ds_write_b128 v86, v[26:29] offset:27648
	s_waitcnt vmcnt(7)
	ds_write_b128 v86, v[30:33] offset:36864
	s_waitcnt vmcnt(6)
	ds_write_b128 v86, v[34:37] offset:46080
	v_mov_b32_e32 v14, v2
	v_mov_b32_e32 v15, v2
	v_mov_b32_e32 v16, v2
	v_mov_b32_e32 v17, v2
	v_mov_b32_e32 v18, v2
	v_mov_b32_e32 v19, v2
	v_mov_b32_e32 v20, v2
	v_mov_b32_e32 v21, v2
	v_mov_b32_e32 v22, v2
	v_mov_b32_e32 v23, v2
	v_mov_b32_e32 v24, v2
	v_mov_b32_e32 v25, v2
	v_mov_b32_e32 v30, v2
	v_mov_b32_e32 v31, v2
	v_mov_b32_e32 v32, v2
	v_mov_b32_e32 v33, v2
	v_mov_b32_e32 v34, v2
	v_mov_b32_e32 v35, v2
	v_mov_b32_e32 v36, v2
	v_mov_b32_e32 v37, v2
	v_mov_b32_e32 v45, v2
	v_mov_b32_e32 v46, v2
	v_mov_b32_e32 v47, v2
	v_mov_b32_e32 v48, v2
	v_mov_b32_e32 v49, v2
	v_mov_b32_e32 v50, v2
	v_mov_b32_e32 v51, v2
	v_mov_b32_e32 v52, v2
	v_mov_b32_e32 v53, v2
	v_mov_b32_e32 v26, v2
	v_mov_b32_e32 v27, v2
	v_mov_b32_e32 v28, v2
	v_mov_b32_e32 v29, v2
	v_mov_b32_e32 v54, v2
	v_mov_b32_e32 v55, v2
	v_mov_b32_e32 v56, v2
	v_mov_b32_e32 v57, v2
	v_mov_b32_e32 v58, v2
	v_mov_b32_e32 v59, v2
	v_mov_b32_e32 v60, v2
	v_mov_b32_e32 v61, v2
	v_mov_b32_e32 v62, v2
	v_mov_b32_e32 v63, v2
	v_mov_b32_e32 v64, v2
	v_mov_b32_e32 v65, v2
	s_waitcnt lgkmcnt(0)
	s_barrier
.LBB0_905:
	s_bitcmp1_b32 s15, 0
	s_cbranch_scc1 .Ld_ld_odd
	v_lshl_add_u64 v[196:197], v[228:229], 0, s[8:9]
	global_load_dwordx4 v[148:151], v[196:197], off offset:2048
	v_lshl_add_u64 v[198:199], v[230:231], 0, s[8:9]
	global_load_dwordx4 v[152:155], v[198:199], off offset:2048
	v_lshl_add_u64 v[196:197], v[232:233], 0, s[8:9]
	global_load_dwordx4 v[156:159], v[196:197], off offset:2048
	v_lshl_add_u64 v[198:199], v[234:235], 0, s[8:9]
	global_load_dwordx4 v[160:163], v[198:199], off offset:2048
	v_lshl_add_u64 v[196:197], v[236:237], 0, s[8:9]
	global_load_dwordx4 v[164:167], v[196:197], off offset:256
	v_lshl_add_u64 v[198:199], v[238:239], 0, s[8:9]
	global_load_dwordx4 v[168:171], v[198:199], off offset:256
	s_branch .Ld_ld_done
.Ld_ld_odd:
	v_lshl_add_u64 v[196:197], v[228:229], 0, s[8:9]
	global_load_dwordx4 v[172:175], v[196:197], off offset:2048
	v_lshl_add_u64 v[198:199], v[230:231], 0, s[8:9]
	global_load_dwordx4 v[176:179], v[198:199], off offset:2048
	v_lshl_add_u64 v[196:197], v[232:233], 0, s[8:9]
	global_load_dwordx4 v[180:183], v[196:197], off offset:2048
	v_lshl_add_u64 v[198:199], v[234:235], 0, s[8:9]
	global_load_dwordx4 v[184:187], v[198:199], off offset:2048
	v_lshl_add_u64 v[196:197], v[236:237], 0, s[8:9]
	global_load_dwordx4 v[188:191], v[196:197], off offset:256
	v_lshl_add_u64 v[198:199], v[238:239], 0, s[8:9]
	global_load_dwordx4 v[192:195], v[198:199], off offset:256
.Ld_ld_done:
	s_add_i32 s22, s15, 1
	s_bitcmp1_b32 s15, 0
	s_cselect_b32 s0, 0xd800, 0
	s_addk_i32 s0, 0xf0
	v_add_u32_e32 v74, s0, v85
	v_add_u32_e32 v87, s0, v84
	ds_read_b128 v[88:91], v74 offset:36864
	ds_read_b128 v[92:95], v87
	ds_read_b128 v[108:111], v74 offset:36928
	ds_read_b128 v[112:115], v87 offset:64
	ds_read_b128 v[116:119], v74 offset:39168
	ds_read_b128 v[66:69], v74 offset:39232
	ds_read_b128 v[120:123], v74 offset:41472
	ds_read_b128 v[70:73], v74 offset:41536
	ds_read_b128 v[124:127], v74 offset:43776
	ds_read_b128 v[74:77], v74 offset:43840
	s_waitcnt lgkmcnt(8)
	v_mfma_f32_16x16x32_bf16 v[50:53], v[88:91], v[92:95], v[50:53]
	s_waitcnt lgkmcnt(5)
	v_mfma_f32_16x16x32_bf16 v[46:49], v[116:119], v[92:95], v[46:49]
	s_waitcnt lgkmcnt(3)
	v_mfma_f32_16x16x32_bf16 v[42:45], v[120:123], v[92:95], v[42:45]
	s_bitcmp1_b32 s22, 0
	s_waitcnt lgkmcnt(1)
	v_mfma_f32_16x16x32_bf16 v[38:41], v[124:127], v[92:95], v[38:41]
	ds_read_b128 v[92:95], v87 offset:2304
	ds_read_b128 v[136:139], v87 offset:2368
	s_waitcnt lgkmcnt(1)
	v_mfma_f32_16x16x32_bf16 v[34:37], v[88:91], v[92:95], v[34:37]
	v_mfma_f32_16x16x32_bf16 v[30:33], v[116:119], v[92:95], v[30:33]
	v_mfma_f32_16x16x32_bf16 v[22:25], v[120:123], v[92:95], v[22:25]
	v_mfma_f32_16x16x32_bf16 v[18:21], v[124:127], v[92:95], v[18:21]
	ds_read_b128 v[92:95], v87 offset:4608
	ds_read_b128 v[140:143], v87 offset:4672
	s_waitcnt lgkmcnt(1)
	v_mfma_f32_16x16x32_bf16 v[14:17], v[88:91], v[92:95], v[14:17]
	v_mfma_f32_16x16x32_bf16 v[10:13], v[116:119], v[92:95], v[10:13]
	v_mfma_f32_16x16x32_bf16 v[6:9], v[120:123], v[92:95], v[6:9]
	v_mfma_f32_16x16x32_bf16 v[2:5], v[124:127], v[92:95], v[2:5]
	ds_read_b128 v[92:95], v87 offset:6912
	ds_read_b128 v[144:147], v87 offset:6976
	s_waitcnt lgkmcnt(1)
	v_mfma_f32_16x16x32_bf16 v[26:29], v[88:91], v[92:95], v[26:29]
	v_mfma_f32_16x16x32_bf16 v[54:57], v[116:119], v[92:95], v[54:57]
	v_mfma_f32_16x16x32_bf16 v[58:61], v[120:123], v[92:95], v[58:61]
	v_mfma_f32_16x16x32_bf16 v[62:65], v[124:127], v[92:95], v[62:65]
	v_mfma_f32_16x16x32_bf16 v[50:53], v[108:111], v[112:115], v[50:53]
	s_mov_b32 s15, s22
	v_mfma_f32_16x16x32_bf16 v[46:49], v[66:69], v[112:115], v[46:49]
	v_mfma_f32_16x16x32_bf16 v[42:45], v[70:73], v[112:115], v[42:45]
	v_mfma_f32_16x16x32_bf16 v[38:41], v[74:77], v[112:115], v[38:41]
	v_mfma_f32_16x16x32_bf16 v[34:37], v[108:111], v[136:139], v[34:37]
	v_mfma_f32_16x16x32_bf16 v[14:17], v[108:111], v[140:143], v[14:17]
	s_waitcnt lgkmcnt(0)
	v_mfma_f32_16x16x32_bf16 v[26:29], v[108:111], v[144:147], v[26:29]
	s_cselect_b32 s0, 0xd800, 0
	s_add_u32 s8, s8, 0x80
	v_mfma_f32_16x16x32_bf16 v[30:33], v[66:69], v[136:139], v[30:33]
	s_addc_u32 s9, s9, 0
	v_mfma_f32_16x16x32_bf16 v[22:25], v[70:73], v[136:139], v[22:25]
	v_mfma_f32_16x16x32_bf16 v[18:21], v[74:77], v[136:139], v[18:21]
	v_mfma_f32_16x16x32_bf16 v[10:13], v[66:69], v[140:143], v[10:13]
	v_mfma_f32_16x16x32_bf16 v[6:9], v[70:73], v[140:143], v[6:9]
	v_mfma_f32_16x16x32_bf16 v[2:5], v[74:77], v[140:143], v[2:5]
	v_mfma_f32_16x16x32_bf16 v[54:57], v[66:69], v[144:147], v[54:57]
	v_add_u32_e32 v66, s0, v86
	s_waitcnt vmcnt(6)
	s_bitcmp1_b32 s22, 0
	s_cbranch_scc1 .Ld_wr_odd
	ds_write_b128 v66, v[148:151]
	ds_write_b128 v66, v[152:155] offset:9216
	ds_write_b128 v66, v[156:159] offset:18432
	ds_write_b128 v66, v[160:163] offset:27648
	ds_write_b128 v66, v[164:167] offset:36864
	ds_write_b128 v66, v[168:171] offset:46080
	s_branch .Ld_wr_done
.Ld_wr_odd:
	ds_write_b128 v66, v[172:175]
	ds_write_b128 v66, v[176:179] offset:9216
	ds_write_b128 v66, v[180:183] offset:18432
	ds_write_b128 v66, v[184:187] offset:27648
	ds_write_b128 v66, v[188:191] offset:36864
	ds_write_b128 v66, v[192:195] offset:46080
.Ld_wr_done:
	v_mfma_f32_16x16x32_bf16 v[58:61], v[70:73], v[144:147], v[58:61]
	s_waitcnt lgkmcnt(0)
	s_barrier
	v_mfma_f32_16x16x32_bf16 v[62:65], v[74:77], v[144:147], v[62:65]
	s_cmpk_lg_i32 s8, 0x780
	s_cbranch_scc1 .LBB0_905
	v_add_u32_e32 v66, 0xf0, v85
	v_add_u32_e32 v96, 0xd800, v66
	ds_read_b128 v[66:69], v96 offset:36864
	ds_read_b128 v[74:77], v96 offset:39168
	v_add_u32_e32 v97, 0xf0, v84
	ds_read_b128 v[80:83], v96 offset:41472
	ds_read_b128 v[84:87], v96 offset:43776
	ds_read_b128 v[70:73], v97 offset:55296
	s_lshl_b32 s54, s14, 8
	v_readlane_b32 s8, v254, 55
	v_readlane_b32 s9, v254, 56
	s_waitcnt lgkmcnt(0)
	v_mfma_f32_16x16x32_bf16 v[50:53], v[66:69], v[70:73], v[50:53]
	s_mov_b64 s[0:1], -1
	s_and_b64 vcc, exec, s[8:9]
	ds_read_b128 v[124:127], v96 offset:41536
	v_mfma_f32_16x16x32_bf16 v[46:49], v[74:77], v[70:73], v[46:49]
	ds_read_b128 v[136:139], v96 offset:43840
	v_mfma_f32_16x16x32_bf16 v[42:45], v[80:83], v[70:73], v[42:45]
	v_mfma_f32_16x16x32_bf16 v[38:41], v[84:87], v[70:73], v[38:41]
	ds_read_b128 v[70:73], v97 offset:57600
	s_waitcnt lgkmcnt(0)
	v_mfma_f32_16x16x32_bf16 v[34:37], v[66:69], v[70:73], v[34:37]
	v_mfma_f32_16x16x32_bf16 v[88:91], v[74:77], v[70:73], v[30:33]
	v_mfma_f32_16x16x32_bf16 v[92:95], v[80:83], v[70:73], v[22:25]
	v_mfma_f32_16x16x32_bf16 v[70:73], v[84:87], v[70:73], v[18:21]
	s_nop 2
	ds_read_b128 v[18:21], v97 offset:59904
	s_waitcnt lgkmcnt(0)
	v_mfma_f32_16x16x32_bf16 v[120:123], v[84:87], v[18:21], v[2:5]
	s_nop 2
	ds_read_b128 v[2:5], v97 offset:62208
	v_mfma_f32_16x16x32_bf16 v[112:115], v[74:77], v[18:21], v[10:13]
	s_waitcnt lgkmcnt(0)
	v_mfma_f32_16x16x32_bf16 v[54:57], v[74:77], v[2:5], v[54:57]
	ds_read_b128 v[74:77], v96 offset:36928
	v_mfma_f32_16x16x32_bf16 v[108:111], v[66:69], v[18:21], v[14:17]
	s_nop 2
	ds_read_b128 v[14:17], v97 offset:55360
	v_mfma_f32_16x16x32_bf16 v[66:69], v[66:69], v[2:5], v[26:29]
	s_nop 2
	ds_read_b128 v[26:29], v97 offset:57664
	s_waitcnt lgkmcnt(1)
	v_mfma_f32_16x16x32_bf16 v[10:13], v[74:77], v[14:17], v[50:53]
	s_nop 2
	ds_read_b128 v[50:53], v96 offset:39232
	v_mfma_f32_16x16x32_bf16 v[58:61], v[80:83], v[2:5], v[58:61]
	v_mfma_f32_16x16x32_bf16 v[84:87], v[84:87], v[2:5], v[62:65]
	v_mfma_f32_16x16x32_bf16 v[2:5], v[124:127], v[14:17], v[42:45]
	s_waitcnt lgkmcnt(0)
	v_mfma_f32_16x16x32_bf16 v[22:25], v[50:53], v[26:29], v[88:91]
	s_nop 0
	ds_read_b128 v[42:45], v97 offset:59968
	s_nop 0
	ds_read_b128 v[88:91], v97 offset:62272
	v_mfma_f32_16x16x32_bf16 v[116:119], v[80:83], v[18:21], v[6:9]
	s_waitcnt lgkmcnt(0)
	s_barrier
	v_mfma_f32_16x16x32_bf16 v[62:65], v[74:77], v[88:91], v[66:69]
	s_nop 2
	ds_read_b128 v[66:69], v131
	v_mfma_f32_16x16x32_bf16 v[6:9], v[50:53], v[14:17], v[46:49]
	v_mfma_f32_16x16x32_bf16 v[14:17], v[136:139], v[14:17], v[38:41]
	v_mfma_f32_16x16x32_bf16 v[30:33], v[74:77], v[26:29], v[34:37]
	v_mfma_f32_16x16x32_bf16 v[18:21], v[124:127], v[26:29], v[92:95]
	v_mfma_f32_16x16x32_bf16 v[26:29], v[136:139], v[26:29], v[70:73]
	v_mfma_f32_16x16x32_bf16 v[46:49], v[74:77], v[42:45], v[108:111]
	s_nop 1
	v_add_u32_e32 v72, s54, v98
	v_or_b32_e32 v82, v72, v1
	v_mfma_f32_16x16x32_bf16 v[38:41], v[50:53], v[42:45], v[112:115]
	v_mfma_f32_16x16x32_bf16 v[34:37], v[124:127], v[42:45], v[116:119]
	v_mfma_f32_16x16x32_bf16 v[42:45], v[136:139], v[42:45], v[120:123]
	v_mfma_f32_16x16x32_bf16 v[54:57], v[50:53], v[88:91], v[54:57]
	v_mfma_f32_16x16x32_bf16 v[50:53], v[124:127], v[88:91], v[58:61]
	v_mfma_f32_16x16x32_bf16 v[58:61], v[136:139], v[88:91], v[84:87]
	s_waitcnt lgkmcnt(0)
	s_nop 7
	s_nop 7
	s_and_b32 s14, s53, 31
	s_lshr_b32 s20, s53, 5
	s_sub_u32 s0, s14, 16
	s_lshr_b32 s0, s0, 2
	s_add_u32 s0, s0, 1
	s_cmp_lt_u32 s14, 16
	s_cselect_b32 s15, 0, s0
	ds_read_b128 v[74:77], v131
	s_add_u32 s0, s52, s15
	s_mul_i32 s0, s0, 0x3000
	s_add_u32 s0, s0, 0x2000
	s_add_u32 s22, s80, s0
	s_addc_u32 s23, s81, 0
	v_and_b32_e32 v66, 63, v0
	v_lshrrev_b32_e32 v67, 6, v0
	v_and_b32_e32 v68, 15, v66
	v_lshrrev_b32_e32 v69, 4, v66
	v_lshrrev_b32_e32 v70, 1, v67
	v_and_b32_e32 v71, 1, v67
	v_lshl_add_u32 v72, v70, 6, v68
	v_lshlrev_b32_e32 v73, 8, v71
	v_lshl_add_u32 v73, v69, 4, v73
	s_lshl_b32 s0, s20, 9
	v_add_u32_e32 v73, s0, v73
	s_waitcnt lgkmcnt(0)
	v_readfirstlane_b32 s8, v74
	v_readfirstlane_b32 s9, v75
	v_readfirstlane_b32 s54, v76
	v_readfirstlane_b32 s55, v77
	s_lshl_b32 s0, s14, 20
	s_cmp_eq_u32 s52, 0
	s_cbranch_scc1 .Ld_epi_l0
	s_mov_b32 s8, s16
	s_mov_b32 s9, s17
	s_branch .Ld_epi_xb
.Ld_epi_l0:
	s_cmp_lt_u32 s14, 16
	s_cbranch_scc1 .Ld_epi_xb
	s_mov_b32 s8, s54
	s_mov_b32 s9, s55
	s_sub_u32 s0, s0, 0x1000000
.Ld_epi_xb:
	s_add_u32 s8, s8, s0
	s_addc_u32 s9, s9, 0
	v_lshl_add_u32 v80, v72, 12, v73
	v_add_u32_e32 v81, 0x10000, v80
	v_add_u32_e32 v82, 0x20000, v80
	v_add_u32_e32 v83, 0x30000, v80
	global_load_dwordx4 v[236:239], v73, s[22:23] offset:0
	global_load_dwordx4 v[240:243], v73, s[22:23] offset:64
	global_load_dwordx4 v[244:247], v73, s[22:23] offset:128
	global_load_dwordx4 v[248:251], v73, s[22:23] offset:192
	global_load_dwordx4 v[148:151], v80, s[8:9] offset:0 nt
	global_load_dwordx4 v[152:155], v80, s[8:9] offset:64 nt
	global_load_dwordx4 v[156:159], v80, s[8:9] offset:128 nt
	global_load_dwordx4 v[160:163], v80, s[8:9] offset:192 nt
	global_load_dwordx4 v[164:167], v81, s[8:9] offset:0 nt
	global_load_dwordx4 v[168:171], v81, s[8:9] offset:64 nt
	global_load_dwordx4 v[172:175], v81, s[8:9] offset:128 nt
	global_load_dwordx4 v[176:179], v81, s[8:9] offset:192 nt
	global_load_dwordx4 v[180:183], v82, s[8:9] offset:0 nt
	global_load_dwordx4 v[184:187], v82, s[8:9] offset:64 nt
	global_load_dwordx4 v[188:191], v82, s[8:9] offset:128 nt
	global_load_dwordx4 v[192:195], v82, s[8:9] offset:192 nt
	global_load_dwordx4 v[196:199], v83, s[8:9] offset:0 nt
	global_load_dwordx4 v[200:203], v83, s[8:9] offset:64 nt
	global_load_dwordx4 v[228:231], v83, s[8:9] offset:128 nt
	global_load_dwordx4 v[232:235], v83, s[8:9] offset:192 nt
	v_lshlrev_b32_e32 v84, 5, v72
	v_lshl_add_u32 v84, v71, 4, v84
	v_lshl_add_u32 v84, v69, 2, v84
	v_add_u32_e32 v84, 0xf0, v84
	s_waitcnt vmcnt(12)
	v_pk_fma_f32 v[10:11], v[10:11], v[236:237], v[148:149]
	v_pk_fma_f32 v[12:13], v[12:13], v[238:239], v[150:151]
	v_pk_fma_f32 v[6:7], v[6:7], v[240:241], v[152:153]
	v_pk_fma_f32 v[8:9], v[8:9], v[242:243], v[154:155]
	v_pk_fma_f32 v[2:3], v[2:3], v[244:245], v[156:157]
	v_pk_fma_f32 v[4:5], v[4:5], v[246:247], v[158:159]
	v_pk_fma_f32 v[14:15], v[14:15], v[248:249], v[160:161]
	v_pk_fma_f32 v[16:17], v[16:17], v[250:251], v[162:163]
	v_pk_mul_f32 v[86:87], v[10:11], v[10:11]
	v_pk_mul_f32 v[88:89], v[12:13], v[12:13]
	v_pk_fma_f32 v[86:87], v[6:7], v[6:7], v[86:87]
	v_pk_fma_f32 v[88:89], v[8:9], v[8:9], v[88:89]
	v_pk_fma_f32 v[86:87], v[2:3], v[2:3], v[86:87]
	v_pk_fma_f32 v[88:89], v[4:5], v[4:5], v[88:89]
	v_pk_fma_f32 v[86:87], v[14:15], v[14:15], v[86:87]
	v_pk_fma_f32 v[88:89], v[16:17], v[16:17], v[88:89]
	s_nop 0
	v_pk_add_f32 v[86:87], v[86:87], v[88:89]
	s_nop 0
	v_add_f32_e32 v86, v86, v87
	ds_write_b32 v84, v86
	s_waitcnt vmcnt(8)
	v_pk_fma_f32 v[30:31], v[30:31], v[236:237], v[164:165]
	v_pk_fma_f32 v[32:33], v[32:33], v[238:239], v[166:167]
	v_pk_fma_f32 v[22:23], v[22:23], v[240:241], v[168:169]
	v_pk_fma_f32 v[24:25], v[24:25], v[242:243], v[170:171]
	v_pk_fma_f32 v[18:19], v[18:19], v[244:245], v[172:173]
	v_pk_fma_f32 v[20:21], v[20:21], v[246:247], v[174:175]
	v_pk_fma_f32 v[26:27], v[26:27], v[248:249], v[176:177]
	v_pk_fma_f32 v[28:29], v[28:29], v[250:251], v[178:179]
	v_pk_mul_f32 v[86:87], v[30:31], v[30:31]
	v_pk_mul_f32 v[88:89], v[32:33], v[32:33]
	v_pk_fma_f32 v[86:87], v[22:23], v[22:23], v[86:87]
	v_pk_fma_f32 v[88:89], v[24:25], v[24:25], v[88:89]
	v_pk_fma_f32 v[86:87], v[18:19], v[18:19], v[86:87]
	v_pk_fma_f32 v[88:89], v[20:21], v[20:21], v[88:89]
	v_pk_fma_f32 v[86:87], v[26:27], v[26:27], v[86:87]
	v_pk_fma_f32 v[88:89], v[28:29], v[28:29], v[88:89]
	s_nop 0
	v_pk_add_f32 v[86:87], v[86:87], v[88:89]
	s_nop 0
	v_add_f32_e32 v86, v86, v87
	ds_write_b32 v84, v86 offset:512
	s_waitcnt vmcnt(4)
	v_pk_fma_f32 v[46:47], v[46:47], v[236:237], v[180:181]
	v_pk_fma_f32 v[48:49], v[48:49], v[238:239], v[182:183]
	v_pk_fma_f32 v[38:39], v[38:39], v[240:241], v[184:185]
	v_pk_fma_f32 v[40:41], v[40:41], v[242:243], v[186:187]
	v_pk_fma_f32 v[34:35], v[34:35], v[244:245], v[188:189]
	v_pk_fma_f32 v[36:37], v[36:37], v[246:247], v[190:191]
	v_pk_fma_f32 v[42:43], v[42:43], v[248:249], v[192:193]
	v_pk_fma_f32 v[44:45], v[44:45], v[250:251], v[194:195]
	v_pk_mul_f32 v[86:87], v[46:47], v[46:47]
	v_pk_mul_f32 v[88:89], v[48:49], v[48:49]
	v_pk_fma_f32 v[86:87], v[38:39], v[38:39], v[86:87]
	v_pk_fma_f32 v[88:89], v[40:41], v[40:41], v[88:89]
	v_pk_fma_f32 v[86:87], v[34:35], v[34:35], v[86:87]
	v_pk_fma_f32 v[88:89], v[36:37], v[36:37], v[88:89]
	v_pk_fma_f32 v[86:87], v[42:43], v[42:43], v[86:87]
	v_pk_fma_f32 v[88:89], v[44:45], v[44:45], v[88:89]
	s_nop 0
	v_pk_add_f32 v[86:87], v[86:87], v[88:89]
	s_nop 0
	v_add_f32_e32 v86, v86, v87
	ds_write_b32 v84, v86 offset:1024
	s_waitcnt vmcnt(0)
	v_pk_fma_f32 v[62:63], v[62:63], v[236:237], v[196:197]
	v_pk_fma_f32 v[64:65], v[64:65], v[238:239], v[198:199]
	v_pk_fma_f32 v[54:55], v[54:55], v[240:241], v[200:201]
	v_pk_fma_f32 v[56:57], v[56:57], v[242:243], v[202:203]
	v_pk_fma_f32 v[50:51], v[50:51], v[244:245], v[228:229]
	v_pk_fma_f32 v[52:53], v[52:53], v[246:247], v[230:231]
	v_pk_fma_f32 v[58:59], v[58:59], v[248:249], v[232:233]
	v_pk_fma_f32 v[60:61], v[60:61], v[250:251], v[234:235]
	v_pk_mul_f32 v[86:87], v[62:63], v[62:63]
	v_pk_mul_f32 v[88:89], v[64:65], v[64:65]
	v_pk_fma_f32 v[86:87], v[54:55], v[54:55], v[86:87]
	v_pk_fma_f32 v[88:89], v[56:57], v[56:57], v[88:89]
	v_pk_fma_f32 v[86:87], v[50:51], v[50:51], v[86:87]
	v_pk_fma_f32 v[88:89], v[52:53], v[52:53], v[88:89]
	v_pk_fma_f32 v[86:87], v[58:59], v[58:59], v[86:87]
	v_pk_fma_f32 v[88:89], v[60:61], v[60:61], v[88:89]
	s_nop 0
	v_pk_add_f32 v[86:87], v[86:87], v[88:89]
	s_nop 0
	v_add_f32_e32 v86, v86, v87
	ds_write_b32 v84, v86 offset:1536
	s_waitcnt lgkmcnt(0)
	s_barrier
	s_add_u32 s0, s50, s14
	s_lshl_b32 s1, s0, 13
	s_add_u32 s56, s73, s1
	s_addc_u32 s57, s78, 0
	s_lshl_b32 s1, s0, 8
	s_add_u32 s58, s64, s1
	s_addc_u32 s59, s72, 0
	v_cmp_gt_u32_e32 vcc, 0x100, v0
	s_and_saveexec_b64 s[54:55], vcc
	s_cbranch_execz .Ld_epi_x1
	v_lshlrev_b32_e32 v85, 5, v0
	v_add_u32_e32 v86, 0xf0, v85
	ds_read_b128 v[88:91], v86
	ds_read_b128 v[92:95], v86 offset:16
	s_lshl_b32 s1, s20, 2
	v_add_u32_e32 v87, s1, v85
	s_waitcnt lgkmcnt(0)
	v_add_f32_e32 v88, v88, v89
	v_add_f32_e32 v90, v90, v91
	v_add_f32_e32 v92, v92, v93
	v_add_f32_e32 v94, v94, v95
	v_add_f32_e32 v88, v88, v90
	v_add_f32_e32 v92, v92, v94
	v_add_f32_e32 v88, v88, v92
	global_store_dword v87, v88, s[56:57] sc1
.Ld_epi_x1:
	s_or_b64 exec, exec, s[54:55]
	s_waitcnt vmcnt(0)
	s_barrier
	v_cmp_eq_u32_e32 vcc, 0, v0
	s_and_saveexec_b64 s[54:55], vcc
	s_cbranch_execz .Ld_epi_x2
	v_mov_b32_e32 v86, 1
	global_atomic_add v131, v86, s[58:59]
	s_mov_b32 s0, 0x400000
.Ld_epi_spin:
	global_load_dword v86, v131, s[58:59] sc1
	s_waitcnt vmcnt(0)
	v_cmp_lt_u32_e32 vcc, 7, v86
	s_cbranch_vccnz .Ld_epi_spun
	s_sleep 2
	s_sub_u32 s0, s0, 1
	s_cmp_lg_u32 s0, 0
	s_cbranch_scc1 .Ld_epi_spin

.Ld_epi_x2:
	s_or_b64 exec, exec, s[54:55]
	s_barrier
	v_cmp_gt_u32_e32 vcc, 0x100, v0
	s_and_saveexec_b64 s[54:55], vcc
	s_cbranch_execz .Ld_epi_x3
	global_load_dword v88, v85, s[56:57] offset:0 sc1
	global_load_dword v89, v85, s[56:57] offset:4 sc1
	global_load_dword v90, v85, s[56:57] offset:8 sc1
	global_load_dword v91, v85, s[56:57] offset:12 sc1
	global_load_dword v92, v85, s[56:57] offset:16 sc1
	global_load_dword v93, v85, s[56:57] offset:20 sc1
	global_load_dword v94, v85, s[56:57] offset:24 sc1
	global_load_dword v95, v85, s[56:57] offset:28 sc1
	v_mov_b32_e32 v87, 0x358637bd
	s_mov_b32 s0, 0x800000
	s_waitcnt vmcnt(0)
	v_add_f32_e32 v88, 0, v88
	v_add_f32_e32 v88, v88, v89
	v_add_f32_e32 v88, v88, v90
	v_add_f32_e32 v88, v88, v91
	v_add_f32_e32 v88, v88, v92
	v_add_f32_e32 v88, v88, v93
	v_add_f32_e32 v88, v88, v94
	v_add_f32_e32 v88, v88, v95
	v_fmamk_f32 v88, v88, 0x3a800000, v87
	v_cmp_gt_f32_e32 vcc, s0, v88
	v_mul_f32_e32 v89, 0x4b800000, v88
	s_nop 0
	v_cndmask_b32_e32 v88, v88, v89, vcc
	v_rsq_f32_e32 v88, v88
	s_nop 0
	v_mul_f32_e32 v89, 0x45800000, v88
	v_cndmask_b32_e32 v88, v88, v89, vcc
	v_lshlrev_b32_e32 v89, 2, v0
	ds_write_b32 v89, v88 offset:8432
.Ld_epi_x3:
	s_or_b64 exec, exec, s[54:55]
	s_waitcnt lgkmcnt(0)
	s_barrier
	v_lshlrev_b32_e32 v85, 2, v72
	ds_read_b32 v108, v85 offset:8432
	ds_read_b32 v110, v85 offset:8496
	ds_read_b32 v112, v85 offset:8560
	ds_read_b32 v114, v85 offset:8624
	s_cmp_eq_u32 s52, 0
	s_cbranch_scc1 .Ld_epi_g0
	ds_read_b64 v[74:75], v131 offset:216
	s_mov_b32 s0, 0
	s_branch .Ld_epi_g1
.Ld_epi_g0:
	ds_read_b64 v[74:75], v131 offset:72
	s_mov_b32 s0, 0x1000
.Ld_epi_g1:
	s_waitcnt lgkmcnt(0)
	v_readfirstlane_b32 s8, v74
	v_readfirstlane_b32 s9, v75
	s_nop 3
	s_add_u32 s8, s8, s0
	s_addc_u32 s9, s9, 0
	s_lshl_b32 s0, s14, 20
	s_add_u32 s54, s16, s0
	s_addc_u32 s55, s17, 0
	s_nop 1
	global_load_dwordx4 v[148:151], v73, s[8:9] offset:0
	global_load_dwordx4 v[152:155], v73, s[8:9] offset:64
	global_load_dwordx4 v[156:159], v73, s[8:9] offset:128
	global_load_dwordx4 v[160:163], v73, s[8:9] offset:192
	s_cmp_eq_u32 s52, 0
	s_cbranch_scc0 .Ld_epi_last
	s_add_u32 s0, s15, 5
	s_mul_i32 s0, s0, 0x3000
	s_add_u32 s22, s80, s0
	s_addc_u32 s23, s81, 0
	s_add_u32 s56, s22, 0x1000
	s_addc_u32 s57, s23, 0
	global_load_dwordx4 v[164:167], v73, s[22:23] offset:0
	global_load_dwordx4 v[168:171], v73, s[22:23] offset:64
	global_load_dwordx4 v[172:175], v73, s[22:23] offset:128
	global_load_dwordx4 v[176:179], v73, s[22:23] offset:192
	global_load_dwordx4 v[180:183], v73, s[56:57] offset:0
	global_load_dwordx4 v[184:187], v73, s[56:57] offset:64
	global_load_dwordx4 v[188:191], v73, s[56:57] offset:128
	global_load_dwordx4 v[192:195], v73, s[56:57] offset:192
	s_lshl_b32 s0, s14, 19
	s_add_u32 s58, s26, s0
	s_addc_u32 s59, s27, 0
	v_lshlrev_b32_e32 v84, 11, v72
	v_lshrrev_b32_e32 v85, 1, v73
	v_add_u32_e32 v84, v84, v85
	global_store_dwordx4 v80, v[10:13], s[54:55] offset:0
	global_store_dwordx4 v80, v[6:9], s[54:55] offset:64
	global_store_dwordx4 v80, v[2:5], s[54:55] offset:128
	global_store_dwordx4 v80, v[14:17], s[54:55] offset:192
	global_store_dwordx4 v81, v[30:33], s[54:55] offset:0
	global_store_dwordx4 v81, v[22:25], s[54:55] offset:64
	global_store_dwordx4 v81, v[18:21], s[54:55] offset:128
	global_store_dwordx4 v81, v[26:29], s[54:55] offset:192
	global_store_dwordx4 v82, v[46:49], s[54:55] offset:0
	global_store_dwordx4 v82, v[38:41], s[54:55] offset:64
	global_store_dwordx4 v82, v[34:37], s[54:55] offset:128
	global_store_dwordx4 v82, v[42:45], s[54:55] offset:192
	global_store_dwordx4 v83, v[62:65], s[54:55] offset:0
	global_store_dwordx4 v83, v[54:57], s[54:55] offset:64
	global_store_dwordx4 v83, v[50:53], s[54:55] offset:128
	global_store_dwordx4 v83, v[58:61], s[54:55] offset:192
	s_waitcnt vmcnt(16)
	v_pk_add_f32 v[180:181], v[180:181], 1.0 op_sel_hi:[1,0]
	v_pk_add_f32 v[182:183], v[182:183], 1.0 op_sel_hi:[1,0]
	v_pk_add_f32 v[184:185], v[184:185], 1.0 op_sel_hi:[1,0]
	v_pk_add_f32 v[186:187], v[186:187], 1.0 op_sel_hi:[1,0]
	v_pk_add_f32 v[188:189], v[188:189], 1.0 op_sel_hi:[1,0]
	v_pk_add_f32 v[190:191], v[190:191], 1.0 op_sel_hi:[1,0]
	v_pk_add_f32 v[192:193], v[192:193], 1.0 op_sel_hi:[1,0]
	v_pk_add_f32 v[194:195], v[194:195], 1.0 op_sel_hi:[1,0]
	v_pk_mul_f32 v[148:149], v[148:149], v[180:181]
	v_pk_mul_f32 v[150:151], v[150:151], v[182:183]
	v_pk_mul_f32 v[152:153], v[152:153], v[184:185]
	v_pk_mul_f32 v[154:155], v[154:155], v[186:187]
	v_pk_mul_f32 v[156:157], v[156:157], v[188:189]
	v_pk_mul_f32 v[158:159], v[158:159], v[190:191]
	v_pk_mul_f32 v[160:161], v[160:161], v[192:193]
	v_pk_mul_f32 v[162:163], v[162:163], v[194:195]
	v_pk_mul_f32 v[10:11], v[10:11], v[108:109] op_sel_hi:[1,0]
	v_pk_mul_f32 v[12:13], v[12:13], v[108:109] op_sel_hi:[1,0]
	v_pk_fma_f32 v[10:11], v[10:11], v[148:149], v[164:165]
	v_pk_fma_f32 v[12:13], v[12:13], v[150:151], v[166:167]
	v_cvt_pk_bf16_f32 v10, v10, v11
	v_cvt_pk_bf16_f32 v11, v12, v13
	global_store_dwordx2 v84, v[10:11], s[58:59] offset:0
	v_pk_mul_f32 v[6:7], v[6:7], v[108:109] op_sel_hi:[1,0]
	v_pk_mul_f32 v[8:9], v[8:9], v[108:109] op_sel_hi:[1,0]
	v_pk_fma_f32 v[6:7], v[6:7], v[152:153], v[168:169]
	v_pk_fma_f32 v[8:9], v[8:9], v[154:155], v[170:171]
	v_cvt_pk_bf16_f32 v6, v6, v7
	v_cvt_pk_bf16_f32 v7, v8, v9
	global_store_dwordx2 v84, v[6:7], s[58:59] offset:32
	v_pk_mul_f32 v[2:3], v[2:3], v[108:109] op_sel_hi:[1,0]
	v_pk_mul_f32 v[4:5], v[4:5], v[108:109] op_sel_hi:[1,0]
	v_pk_fma_f32 v[2:3], v[2:3], v[156:157], v[172:173]
	v_pk_fma_f32 v[4:5], v[4:5], v[158:159], v[174:175]
	v_cvt_pk_bf16_f32 v2, v2, v3
	v_cvt_pk_bf16_f32 v3, v4, v5
	global_store_dwordx2 v84, v[2:3], s[58:59] offset:64
	v_pk_mul_f32 v[14:15], v[14:15], v[108:109] op_sel_hi:[1,0]
	v_pk_mul_f32 v[16:17], v[16:17], v[108:109] op_sel_hi:[1,0]
	v_pk_fma_f32 v[14:15], v[14:15], v[160:161], v[176:177]
	v_pk_fma_f32 v[16:17], v[16:17], v[162:163], v[178:179]
	v_cvt_pk_bf16_f32 v14, v14, v15
	v_cvt_pk_bf16_f32 v15, v16, v17
	global_store_dwordx2 v84, v[14:15], s[58:59] offset:96
	v_add_u32_e32 v84, 0x8000, v84
	v_pk_mul_f32 v[30:31], v[30:31], v[110:111] op_sel_hi:[1,0]
	v_pk_mul_f32 v[32:33], v[32:33], v[110:111] op_sel_hi:[1,0]
	v_pk_fma_f32 v[30:31], v[30:31], v[148:149], v[164:165]
	v_pk_fma_f32 v[32:33], v[32:33], v[150:151], v[166:167]
	v_cvt_pk_bf16_f32 v30, v30, v31
	v_cvt_pk_bf16_f32 v31, v32, v33
	global_store_dwordx2 v84, v[30:31], s[58:59] offset:0
	v_pk_mul_f32 v[22:23], v[22:23], v[110:111] op_sel_hi:[1,0]
	v_pk_mul_f32 v[24:25], v[24:25], v[110:111] op_sel_hi:[1,0]
	v_pk_fma_f32 v[22:23], v[22:23], v[152:153], v[168:169]
	v_pk_fma_f32 v[24:25], v[24:25], v[154:155], v[170:171]
	v_cvt_pk_bf16_f32 v22, v22, v23
	v_cvt_pk_bf16_f32 v23, v24, v25
	global_store_dwordx2 v84, v[22:23], s[58:59] offset:32
	v_pk_mul_f32 v[18:19], v[18:19], v[110:111] op_sel_hi:[1,0]
	v_pk_mul_f32 v[20:21], v[20:21], v[110:111] op_sel_hi:[1,0]
	v_pk_fma_f32 v[18:19], v[18:19], v[156:157], v[172:173]
	v_pk_fma_f32 v[20:21], v[20:21], v[158:159], v[174:175]
	v_cvt_pk_bf16_f32 v18, v18, v19
	v_cvt_pk_bf16_f32 v19, v20, v21
	global_store_dwordx2 v84, v[18:19], s[58:59] offset:64
	v_pk_mul_f32 v[26:27], v[26:27], v[110:111] op_sel_hi:[1,0]
	v_pk_mul_f32 v[28:29], v[28:29], v[110:111] op_sel_hi:[1,0]
	v_pk_fma_f32 v[26:27], v[26:27], v[160:161], v[176:177]
	v_pk_fma_f32 v[28:29], v[28:29], v[162:163], v[178:179]
	v_cvt_pk_bf16_f32 v26, v26, v27
	v_cvt_pk_bf16_f32 v27, v28, v29
	global_store_dwordx2 v84, v[26:27], s[58:59] offset:96
	v_add_u32_e32 v84, 0x8000, v84
	v_pk_mul_f32 v[46:47], v[46:47], v[112:113] op_sel_hi:[1,0]
	v_pk_mul_f32 v[48:49], v[48:49], v[112:113] op_sel_hi:[1,0]
	v_pk_fma_f32 v[46:47], v[46:47], v[148:149], v[164:165]
	v_pk_fma_f32 v[48:49], v[48:49], v[150:151], v[166:167]
	v_cvt_pk_bf16_f32 v46, v46, v47
	v_cvt_pk_bf16_f32 v47, v48, v49
	global_store_dwordx2 v84, v[46:47], s[58:59] offset:0
	v_pk_mul_f32 v[38:39], v[38:39], v[112:113] op_sel_hi:[1,0]
	v_pk_mul_f32 v[40:41], v[40:41], v[112:113] op_sel_hi:[1,0]
	v_pk_fma_f32 v[38:39], v[38:39], v[152:153], v[168:169]
	v_pk_fma_f32 v[40:41], v[40:41], v[154:155], v[170:171]
	v_cvt_pk_bf16_f32 v38, v38, v39
	v_cvt_pk_bf16_f32 v39, v40, v41
	global_store_dwordx2 v84, v[38:39], s[58:59] offset:32
	v_pk_mul_f32 v[34:35], v[34:35], v[112:113] op_sel_hi:[1,0]
	v_pk_mul_f32 v[36:37], v[36:37], v[112:113] op_sel_hi:[1,0]
	v_pk_fma_f32 v[34:35], v[34:35], v[156:157], v[172:173]
	v_pk_fma_f32 v[36:37], v[36:37], v[158:159], v[174:175]
	v_cvt_pk_bf16_f32 v34, v34, v35
	v_cvt_pk_bf16_f32 v35, v36, v37
	global_store_dwordx2 v84, v[34:35], s[58:59] offset:64
	v_pk_mul_f32 v[42:43], v[42:43], v[112:113] op_sel_hi:[1,0]
	v_pk_mul_f32 v[44:45], v[44:45], v[112:113] op_sel_hi:[1,0]
	v_pk_fma_f32 v[42:43], v[42:43], v[160:161], v[176:177]
	v_pk_fma_f32 v[44:45], v[44:45], v[162:163], v[178:179]
	v_cvt_pk_bf16_f32 v42, v42, v43
	v_cvt_pk_bf16_f32 v43, v44, v45
	global_store_dwordx2 v84, v[42:43], s[58:59] offset:96
	v_add_u32_e32 v84, 0x8000, v84
	v_pk_mul_f32 v[62:63], v[62:63], v[114:115] op_sel_hi:[1,0]
	v_pk_mul_f32 v[64:65], v[64:65], v[114:115] op_sel_hi:[1,0]
	v_pk_fma_f32 v[62:63], v[62:63], v[148:149], v[164:165]
	v_pk_fma_f32 v[64:65], v[64:65], v[150:151], v[166:167]
	v_cvt_pk_bf16_f32 v62, v62, v63
	v_cvt_pk_bf16_f32 v63, v64, v65
	global_store_dwordx2 v84, v[62:63], s[58:59] offset:0
	v_pk_mul_f32 v[54:55], v[54:55], v[114:115] op_sel_hi:[1,0]
	v_pk_mul_f32 v[56:57], v[56:57], v[114:115] op_sel_hi:[1,0]
	v_pk_fma_f32 v[54:55], v[54:55], v[152:153], v[168:169]
	v_pk_fma_f32 v[56:57], v[56:57], v[154:155], v[170:171]
	v_cvt_pk_bf16_f32 v54, v54, v55
	v_cvt_pk_bf16_f32 v55, v56, v57
	global_store_dwordx2 v84, v[54:55], s[58:59] offset:32
	v_pk_mul_f32 v[50:51], v[50:51], v[114:115] op_sel_hi:[1,0]
	v_pk_mul_f32 v[52:53], v[52:53], v[114:115] op_sel_hi:[1,0]
	v_pk_fma_f32 v[50:51], v[50:51], v[156:157], v[172:173]
	v_pk_fma_f32 v[52:53], v[52:53], v[158:159], v[174:175]
	v_cvt_pk_bf16_f32 v50, v50, v51
	v_cvt_pk_bf16_f32 v51, v52, v53
	global_store_dwordx2 v84, v[50:51], s[58:59] offset:64
	v_pk_mul_f32 v[58:59], v[58:59], v[114:115] op_sel_hi:[1,0]
	v_pk_mul_f32 v[60:61], v[60:61], v[114:115] op_sel_hi:[1,0]
	v_pk_fma_f32 v[58:59], v[58:59], v[160:161], v[176:177]
	v_pk_fma_f32 v[60:61], v[60:61], v[162:163], v[178:179]
	v_cvt_pk_bf16_f32 v58, v58, v59
	v_cvt_pk_bf16_f32 v59, v60, v61
	global_store_dwordx2 v84, v[58:59], s[58:59] offset:96
	s_branch .LBB0_893
.Ld_epi_last:
	s_waitcnt vmcnt(0)
	v_pk_mul_f32 v[10:11], v[10:11], v[108:109] op_sel_hi:[1,0]
	v_pk_mul_f32 v[12:13], v[12:13], v[108:109] op_sel_hi:[1,0]
	v_pk_mul_f32 v[10:11], v[10:11], v[148:149]
	v_pk_mul_f32 v[12:13], v[12:13], v[150:151]
	global_store_dwordx4 v80, v[10:13], s[54:55] offset:0
	v_pk_mul_f32 v[6:7], v[6:7], v[108:109] op_sel_hi:[1,0]
	v_pk_mul_f32 v[8:9], v[8:9], v[108:109] op_sel_hi:[1,0]
	v_pk_mul_f32 v[6:7], v[6:7], v[152:153]
	v_pk_mul_f32 v[8:9], v[8:9], v[154:155]
	global_store_dwordx4 v80, v[6:9], s[54:55] offset:64
	v_pk_mul_f32 v[2:3], v[2:3], v[108:109] op_sel_hi:[1,0]
	v_pk_mul_f32 v[4:5], v[4:5], v[108:109] op_sel_hi:[1,0]
	v_pk_mul_f32 v[2:3], v[2:3], v[156:157]
	v_pk_mul_f32 v[4:5], v[4:5], v[158:159]
	global_store_dwordx4 v80, v[2:5], s[54:55] offset:128
	v_pk_mul_f32 v[14:15], v[14:15], v[108:109] op_sel_hi:[1,0]
	v_pk_mul_f32 v[16:17], v[16:17], v[108:109] op_sel_hi:[1,0]
	v_pk_mul_f32 v[14:15], v[14:15], v[160:161]
	v_pk_mul_f32 v[16:17], v[16:17], v[162:163]
	global_store_dwordx4 v80, v[14:17], s[54:55] offset:192
	v_pk_mul_f32 v[30:31], v[30:31], v[110:111] op_sel_hi:[1,0]
	v_pk_mul_f32 v[32:33], v[32:33], v[110:111] op_sel_hi:[1,0]
	v_pk_mul_f32 v[30:31], v[30:31], v[148:149]
	v_pk_mul_f32 v[32:33], v[32:33], v[150:151]
	global_store_dwordx4 v81, v[30:33], s[54:55] offset:0
	v_pk_mul_f32 v[22:23], v[22:23], v[110:111] op_sel_hi:[1,0]
	v_pk_mul_f32 v[24:25], v[24:25], v[110:111] op_sel_hi:[1,0]
	v_pk_mul_f32 v[22:23], v[22:23], v[152:153]
	v_pk_mul_f32 v[24:25], v[24:25], v[154:155]
	global_store_dwordx4 v81, v[22:25], s[54:55] offset:64
	v_pk_mul_f32 v[18:19], v[18:19], v[110:111] op_sel_hi:[1,0]
	v_pk_mul_f32 v[20:21], v[20:21], v[110:111] op_sel_hi:[1,0]
	v_pk_mul_f32 v[18:19], v[18:19], v[156:157]
	v_pk_mul_f32 v[20:21], v[20:21], v[158:159]
	global_store_dwordx4 v81, v[18:21], s[54:55] offset:128
	v_pk_mul_f32 v[26:27], v[26:27], v[110:111] op_sel_hi:[1,0]
	v_pk_mul_f32 v[28:29], v[28:29], v[110:111] op_sel_hi:[1,0]
	v_pk_mul_f32 v[26:27], v[26:27], v[160:161]
	v_pk_mul_f32 v[28:29], v[28:29], v[162:163]
	global_store_dwordx4 v81, v[26:29], s[54:55] offset:192
	v_pk_mul_f32 v[46:47], v[46:47], v[112:113] op_sel_hi:[1,0]
	v_pk_mul_f32 v[48:49], v[48:49], v[112:113] op_sel_hi:[1,0]
	v_pk_mul_f32 v[46:47], v[46:47], v[148:149]
	v_pk_mul_f32 v[48:49], v[48:49], v[150:151]
	global_store_dwordx4 v82, v[46:49], s[54:55] offset:0
	v_pk_mul_f32 v[38:39], v[38:39], v[112:113] op_sel_hi:[1,0]
	v_pk_mul_f32 v[40:41], v[40:41], v[112:113] op_sel_hi:[1,0]
	v_pk_mul_f32 v[38:39], v[38:39], v[152:153]
	v_pk_mul_f32 v[40:41], v[40:41], v[154:155]
	global_store_dwordx4 v82, v[38:41], s[54:55] offset:64
	v_pk_mul_f32 v[34:35], v[34:35], v[112:113] op_sel_hi:[1,0]
	v_pk_mul_f32 v[36:37], v[36:37], v[112:113] op_sel_hi:[1,0]
	v_pk_mul_f32 v[34:35], v[34:35], v[156:157]
	v_pk_mul_f32 v[36:37], v[36:37], v[158:159]
	global_store_dwordx4 v82, v[34:37], s[54:55] offset:128
	v_pk_mul_f32 v[42:43], v[42:43], v[112:113] op_sel_hi:[1,0]
	v_pk_mul_f32 v[44:45], v[44:45], v[112:113] op_sel_hi:[1,0]
	v_pk_mul_f32 v[42:43], v[42:43], v[160:161]
	v_pk_mul_f32 v[44:45], v[44:45], v[162:163]
	global_store_dwordx4 v82, v[42:45], s[54:55] offset:192
	v_pk_mul_f32 v[62:63], v[62:63], v[114:115] op_sel_hi:[1,0]
	v_pk_mul_f32 v[64:65], v[64:65], v[114:115] op_sel_hi:[1,0]
	v_pk_mul_f32 v[62:63], v[62:63], v[148:149]
	v_pk_mul_f32 v[64:65], v[64:65], v[150:151]
	global_store_dwordx4 v83, v[62:65], s[54:55] offset:0
	v_pk_mul_f32 v[54:55], v[54:55], v[114:115] op_sel_hi:[1,0]
	v_pk_mul_f32 v[56:57], v[56:57], v[114:115] op_sel_hi:[1,0]
	v_pk_mul_f32 v[54:55], v[54:55], v[152:153]
	v_pk_mul_f32 v[56:57], v[56:57], v[154:155]
	global_store_dwordx4 v83, v[54:57], s[54:55] offset:64
	v_pk_mul_f32 v[50:51], v[50:51], v[114:115] op_sel_hi:[1,0]
	v_pk_mul_f32 v[52:53], v[52:53], v[114:115] op_sel_hi:[1,0]
	v_pk_mul_f32 v[50:51], v[50:51], v[156:157]
	v_pk_mul_f32 v[52:53], v[52:53], v[158:159]
	global_store_dwordx4 v83, v[50:53], s[54:55] offset:128
	v_pk_mul_f32 v[58:59], v[58:59], v[114:115] op_sel_hi:[1,0]
	v_pk_mul_f32 v[60:61], v[60:61], v[114:115] op_sel_hi:[1,0]
	v_pk_mul_f32 v[58:59], v[58:59], v[160:161]
	v_pk_mul_f32 v[60:61], v[60:61], v[162:163]
	global_store_dwordx4 v83, v[58:61], s[54:55] offset:192
	s_branch .LBB0_893
